# attn_d: K tile row pitch 528 B in LDS
# baseline (speedup 1.0000x reference)
; template <int DQK, int KA8, int DV, bool BIAS, bool JOINT>
; DI void attn_core(LAS unsigned char* lds, const bf16_t* Qrow, const bf16_t* KpA, int ldkA, const bf16_t* KpB, int ldkB, const bf16_t* Vp, int ldv,
;                   int qb, int wid, int lane, const float* qng  , f32x16 (&O)[DV / 32]) {
;     ...
;     const unsigned koff = l32 * KROW + 16 * hh, vtr = (4 * hh + tq) * VROW + (16 * blk + 4 * tp) * 2;
;     auto gload = [&](int kt) {
; #pragma unroll
;         for (int i = 0; i < NL; ++i) { const int c = tid + i * 512;
;             if (i * 512 < NKC) { const int row = c / KC, cc = c % KC;
;                 const bf16_t* src = (cc < KA8) ? KpA + (size_t)(kt * 64 + row) * ldkA + cc * 8 : KpB + (size_t)(kt * 64 + row) * ldkB + (cc - KA8) * 8;
;                 stg[i] = *(const u32x4*)src; }
;             else { const int c2 = c - NKC, row = c2 / VC, cc = c2 % VC; stg[i] = *(const u32x4*)(Vp + (size_t)(kt * 64 + row) * ldv + cc * 8); } }
;     };
;     auto lstore = [&](int buf) {
; #pragma unroll
;         for (int i = 0; i < NL; ++i) { const int c = tid + i * 512;
;             if (i * 512 < NKC) { const int row = c / KC, cc = c % KC; *(LAS u32x4*)(lds + buf * STG + row * KROW + cc * 16) = stg[i]; }
;             else { const int c2 = c - NKC, row = c2 / VC, cc = c2 % VC; *(LAS u32x4*)(lds + buf * STG + 64 * KROW + row * VROW + cc * 16) = stg[i]; } }
; DI void phase_attn_d(const Params& p, LAS unsigned char* lds) {
;     const bf16_t* qkv = (const bf16_t*)(p.ws + ACT); const bf16_t* lat = (const bf16_t*)(p.ws + LAT); const bf16_t* gb = (const bf16_t*)(p.ws + HBUF);
;     bf16_t* y = (bf16_t*)(p.ws + HBUF);
;     for (int pr = blockIdx.x; pr < 512; pr += gridDim.x) {
;         const int bi = pr & 255, bh = (gridDim.x == 256) ? (bi & 7) + 8 * (bi >> 6) + 32 * (pr >> 8) : pr >> 3, j = (gridDim.x == 256) ? (bi >> 3) & 7 : pr & 7, b = bh >> 4, h = bh & 15;
;         for (int half = 0; half < 2; ++half) {
;             const int qb = half ? 15 - j : j;
;             __syncthreads();
;             const int tid = otid(), wid = tid >> 6, lane = tid & 63, l32 = lane & 31;
;             const size_t tok0 = (size_t)b * SEQ, tokq = tok0 + qb * 256 + wid * 32 + l32;
;             f32x16 O[4];
;             attn_core<192, 16, 128, false, true>(lds, qkv + tokq * 7168 + h * 192, qkv + tok0 * 7168 + 3072 + h * 256, 7168, lat + tok0 * 1088 + 1024, 1088,
.LBB0_1556:
	s_or_b64 exec, exec, s[6:7]
	s_and_b64 vcc, exec, s[4:5]
	s_waitcnt lgkmcnt(0)
	s_barrier
	s_cbranch_vccnz .LBB0_1625
	s_load_dwordx2 s[6:7], s[0:1], 0xf0
	s_load_dwordx2 s[12:13], s[0:1], 0xd8
	v_and_b32_e32 v228, 63, v181
	v_and_b32_e32 v226, 31, v228
	v_lshrrev_b32_e32 v227, 5, v228
	v_mul_u32_u24_e32 v214, 528, v226
	v_lshl_add_u32 v214, v227, 4, v214
	v_bfe_u32 v235, v228, 2, 2
	v_lshl_add_u32 v235, v227, 2, v235
	v_mul_u32_u24_e32 v215, 320, v235
	v_and_b32_e32 v235, 3, v228
	v_lshl_add_u32 v215, v235, 3, v215
	v_bfe_u32 v235, v228, 4, 1
	v_lshl_add_u32 v215, v235, 5, v215
	v_lshrrev_b32_e32 v235, 4, v181
	v_and_b32_e32 v236, 15, v181
	v_mul_u32_u24_e32 v216, 528, v235
	v_lshl_add_u32 v216, v236, 4, v216
	v_mul_u32_u24_e32 v218, 320, v235
	v_lshl_add_u32 v218, v236, 4, v218
	v_mul_u32_u24_e32 v219, 14336, v235
	v_lshl_add_u32 v219, v236, 4, v219
	v_add_u32_e32 v220, 0x70000, v219
	v_mov_b32_e32 v222, v219
	v_mov_b32_e32 v223, v220
	v_lshrrev_b32_e32 v235, 3, v181
	v_and_b32_e32 v236, 7, v181
	v_mul_u32_u24_e32 v217, 528, v235
	v_lshl_add_u32 v217, v236, 4, v217
	v_add_u32_e32 v217, 256, v217
	v_add_u32_e32 v253, 74752, v216
	v_add_u32_e32 v254, 74752, v217
	v_add_u32_e32 v252, 74752, v214
	v_mul_u32_u24_e32 v221, 2176, v235
	v_lshl_add_u32 v221, v236, 4, v221
	v_mul_u32_u24_e32 v237, 14336, v226
	v_lshl_add_u32 v237, v227, 4, v237
	v_lshlrev_b32_e32 v238, 12, v226
	v_lshl_add_u32 v238, v227, 3, v238
	v_lshlrev_b32_e32 v239, 5, v227
	v_lshrrev_b32_e32 v235, 6, v181
	s_nop 0
	v_readfirstlane_b32 s26, v235
	s_waitcnt lgkmcnt(0)
	v_cmp_gt_u32_e32 vcc, 192, v181
	s_and_saveexec_b64 s[66:67], vcc
	s_cbranch_execz .Lad_gnskip
	v_lshlrev_b32_e32 v229, 2, v181
	global_load_dword v230, v229, s[12:13]
	v_add_u32_e32 v229, 108544, v229
	s_waitcnt vmcnt(0)
	ds_write_b32 v229, v230
	s_waitcnt lgkmcnt(0)
.Lad_gnskip:
	s_or_b64 exec, exec, s[66:67]
	v_add_u32_e32 v239, 108544, v239
	s_add_u32 s8, s6, 0xbf00000
	s_addc_u32 s9, s7, 0
	s_add_u32 s10, s6, 0x7f00000
	s_addc_u32 s11, s7, 0
	s_mov_b32 s14, s2

; template <int DQK, int KA8, int DV, bool BIAS, bool JOINT>
; DI void attn_core(LAS unsigned char* lds, const bf16_t* Qrow, const bf16_t* KpA, int ldkA, const bf16_t* KpB, int ldkB, const bf16_t* Vp, int ldv,
;                   int qb, int wid, int lane, const float* qng  , f32x16 (&O)[DV / 32]) {
;     ...
;     const int q0w = qb * 256 + wid * 32, nkt = 4 * qb + 4, myc = q0w >> 6;
;     bf16x8 qf[DQK / 16];
; #pragma unroll
;     for (int s = 0; s < DQK / 16; ++s) qf[s] = *(const bf16x8*)(Qrow + 16 * s + 8 * hh);
;     if constexpr (DQK == 192) {
;         if (qng) {
;             float ssn = 0.f, ssr = 0.f;
; #pragma unroll
;             for (int s = 0; s < 12; ++s) { float f[8]; unpack8(__builtin_bit_cast(u32x4, qf[s]), f); float t = 0.f;
; #pragma unroll
;                 for (int e = 0; e < 8; ++e) t += f[e] * f[e];
;                 if (s < 8) ssn += t; else ssr += t; }
;             ssn += __shfl_xor(ssn, 32); ssr += __shfl_xor(ssr, 32);
;             const float qs = 0.07216878364870322f * LOG2E, scn = rsqrtf(ssn * (1.f / 128.f) + EPS) * qs, scr = rsqrtf(ssr * (1.f / 64.f) + EPS) * qs;
; #pragma unroll
;             for (int s = 0; s < 8; ++s) { float f[8]; unpack8(__builtin_bit_cast(u32x4, qf[s]), f);
;                 const f32x4 g0 = *(const f32x4*)(qng + 16 * s + 8 * hh), g1 = *(const f32x4*)(qng + 16 * s + 8 * hh + 4);
; #pragma unroll
;                 for (int e = 0; e < 4; ++e) { f[e] *= scn * g0[e]; f[4 + e] *= scn * g1[e]; }
;                 qf[s] = __builtin_bit_cast(bf16x8, pack8(f)); }
;             const float posr = (float)(qb * 256 + wid * 32 + l32) * 0.15915494309189535f;
; #pragma unroll
;             for (int s = 8; s < 10; ++s) { float f1[8], f2[8]; unpack8(__builtin_bit_cast(u32x4, qf[s]), f1); unpack8(__builtin_bit_cast(u32x4, qf[s + 2]), f2);
; #pragma unroll
;                 for (int e = 0; e < 8; ++e) { const int i = 16 * (s - 8) + 8 * hh + e;
;                     const float a1 = f1[e] * scr * qng[128 + i], a2 = f2[e] * scr * qng[160 + i];
;                     float rev = posr * __builtin_amdgcn_exp2f(-(float)i * 0.41524101186092029f); rev -= floorf(rev);
;                     const float sn = __builtin_amdgcn_sinf(rev), cs = __builtin_amdgcn_cosf(rev);
;                     f1[e] = a1 * cs - a2 * sn; f2[e] = a2 * cs + a1 * sn; }
.Lad_half:
	s_sub_i32 s58, 15, s29
	s_cmp_eq_u32 s15, 0
	s_cselect_b32 s16, s29, s58
	s_lshl_b32 s17, s16, 2
	s_add_i32 s17, s17, 4
	s_lshl_b32 s43, s16, 8
	s_lshl_b32 s58, s26, 5
	s_add_i32 s43, s43, s58
	s_lshr_b32 s25, s43, 6
	s_lshl_b32 s58, s28, 12
	s_add_i32 s59, s58, s43
	s_mul_i32 s60, s59, 14336
	s_mul_hi_u32 s61, s59, 14336
	s_mul_i32 s42, s27, 384
	s_add_u32 s46, s8, s60
	s_addc_u32 s47, s9, s61
	s_add_u32 s46, s46, s42
	s_addc_u32 s47, s47, 0
	s_mul_i32 s60, s58, 14336
	s_mul_hi_u32 s61, s58, 14336
	s_lshl_b32 s42, s27, 9
	s_add_u32 s48, s8, s60
	s_addc_u32 s49, s9, s61
	s_add_u32 s48, s48, s42
	s_addc_u32 s49, s49, 0
	s_add_u32 s48, s48, 0x1800
	s_addc_u32 s49, s49, 0
	s_add_u32 s50, s48, 0x100
	s_addc_u32 s51, s49, 0
	s_mul_i32 s60, s58, 2176
	s_mul_hi_u32 s61, s58, 2176
	s_add_u32 s52, s6, s60
	s_addc_u32 s53, s7, s61
	s_add_u32 s52, s52, 0x800
	s_addc_u32 s53, s53, 0
	s_mov_b32 s60, s59
	s_mov_b32 s61, 0
	s_lshl_b64 s[60:61], s[60:61], 12
	s_lshl_b32 s42, s27, 8
	s_add_u32 s54, s10, s60
	s_addc_u32 s55, s11, s61
	s_add_u32 s54, s54, s42
	s_addc_u32 s55, s55, 0
	v_add_u32_e32 v229, s43, v226
	v_cvt_f32_u32_e32 v229, v229
	v_mul_f32_e32 v240, 0x3e22f983, v229
	s_barrier
	s_mov_b64 s[30:31], s[48:49]
	s_mov_b64 s[36:37], s[52:53]
	s_mov_b64 s[34:35], s[50:51]
	global_load_dwordx4 v[160:163], v219, s[30:31]
	global_load_dwordx4 v[164:167], v220, s[30:31]
	global_load_dwordx4 v[168:171], v221, s[36:37]
	global_load_dwordx4 v[112:115], v237, s[46:47] offset:0
	global_load_dwordx4 v[116:119], v237, s[46:47] offset:32
	global_load_dwordx4 v[120:123], v237, s[46:47] offset:64
	global_load_dwordx4 v[124:127], v237, s[46:47] offset:96
	global_load_dwordx4 v[128:131], v237, s[46:47] offset:128
	global_load_dwordx4 v[132:135], v237, s[46:47] offset:160
	global_load_dwordx4 v[136:139], v237, s[46:47] offset:192
	global_load_dwordx4 v[140:143], v237, s[46:47] offset:224
	global_load_dwordx4 v[144:147], v237, s[46:47] offset:256
	global_load_dwordx4 v[148:151], v237, s[46:47] offset:288
	global_load_dwordx4 v[152:155], v237, s[46:47] offset:320
	global_load_dwordx4 v[156:159], v237, s[46:47] offset:352
	s_add_u32 s30, s30, 0xe0000
	s_addc_u32 s31, s31, 0
	s_add_u32 s36, s36, 0x22000
	s_addc_u32 s37, s37, 0
	v_mov_b32_e32 v0, 0
	v_mov_b32_e32 v1, 0
	v_mov_b32_e32 v2, 0
	v_mov_b32_e32 v3, 0
	v_mov_b32_e32 v4, 0
	v_mov_b32_e32 v5, 0
	v_mov_b32_e32 v6, 0
	v_mov_b32_e32 v7, 0
	v_mov_b32_e32 v8, 0
	v_mov_b32_e32 v9, 0
	v_mov_b32_e32 v10, 0
	v_mov_b32_e32 v11, 0
	v_mov_b32_e32 v12, 0
	v_mov_b32_e32 v13, 0
	v_mov_b32_e32 v14, 0
	v_mov_b32_e32 v15, 0
	v_mov_b32_e32 v16, 0
	v_mov_b32_e32 v17, 0
	v_mov_b32_e32 v18, 0
	v_mov_b32_e32 v19, 0
	v_mov_b32_e32 v20, 0
	v_mov_b32_e32 v21, 0
	v_mov_b32_e32 v22, 0
	v_mov_b32_e32 v23, 0
	v_mov_b32_e32 v24, 0
	v_mov_b32_e32 v25, 0
	v_mov_b32_e32 v26, 0
	v_mov_b32_e32 v27, 0
	v_mov_b32_e32 v28, 0
	v_mov_b32_e32 v29, 0
	v_mov_b32_e32 v30, 0
	v_mov_b32_e32 v31, 0
	v_mov_b32_e32 v32, 0
	v_mov_b32_e32 v33, 0
	v_mov_b32_e32 v34, 0
	v_mov_b32_e32 v35, 0
	v_mov_b32_e32 v36, 0
	v_mov_b32_e32 v37, 0
	v_mov_b32_e32 v38, 0
	v_mov_b32_e32 v39, 0
	v_mov_b32_e32 v40, 0
	v_mov_b32_e32 v41, 0
	v_mov_b32_e32 v42, 0
	v_mov_b32_e32 v43, 0
	v_mov_b32_e32 v44, 0
	v_mov_b32_e32 v45, 0
	v_mov_b32_e32 v46, 0
	v_mov_b32_e32 v47, 0
	v_mov_b32_e32 v48, 0
	v_mov_b32_e32 v49, 0
	v_mov_b32_e32 v50, 0
	v_mov_b32_e32 v51, 0
	v_mov_b32_e32 v52, 0
	v_mov_b32_e32 v53, 0
	v_mov_b32_e32 v54, 0
	v_mov_b32_e32 v55, 0
	v_mov_b32_e32 v56, 0
	v_mov_b32_e32 v57, 0
	v_mov_b32_e32 v58, 0
	v_mov_b32_e32 v59, 0
	v_mov_b32_e32 v60, 0
	v_mov_b32_e32 v61, 0
	v_mov_b32_e32 v62, 0
	v_mov_b32_e32 v63, 0
	v_mov_b32_e32 v224, 0
	v_mov_b32_e32 v225, 0
	s_mov_b32 s40, 0
	s_waitcnt vmcnt(12)
	ds_write_b128 v216, v[160:163] offset:40960
	ds_write_b128 v216, v[164:167] offset:57856
	ds_write_b128 v217, v[168:171] offset:40960
	s_waitcnt lgkmcnt(0)
	global_load_dwordx4 v[160:163], v219, s[30:31]
	global_load_dwordx4 v[164:167], v220, s[30:31]
	global_load_dwordx4 v[168:171], v221, s[36:37]
	global_load_dwordx4 v[172:175], v222, s[34:35]
	global_load_dwordx4 v[176:179], v223, s[34:35]
	s_add_u32 s30, s30, 0xe0000
	s_addc_u32 s31, s31, 0
	s_add_u32 s36, s36, 0x22000
	s_addc_u32 s37, s37, 0
	s_add_u32 s34, s34, 0xe0000
	s_addc_u32 s35, s35, 0
	s_waitcnt vmcnt(5)
; template <int DQK, int KA8, int DV, bool BIAS, bool JOINT>
; DI void attn_core(LAS unsigned char* lds, const bf16_t* Qrow, const bf16_t* KpA, int ldkA, const bf16_t* KpB, int ldkB, const bf16_t* Vp, int ldv,
;                   int qb, int wid, int lane, const float* qng  , f32x16 (&O)[DV / 32]) {
;     ...
;             float ssn = 0.f, ssr = 0.f;
; #pragma unroll
;             for (int s = 0; s < 12; ++s) { float f[8]; unpack8(__builtin_bit_cast(u32x4, qf[s]), f); float t = 0.f;
; #pragma unroll
;                 for (int e = 0; e < 8; ++e) t += f[e] * f[e];
;                 if (s < 8) ssn += t; else ssr += t; }
;             ssn += __shfl_xor(ssn, 32); ssr += __shfl_xor(ssr, 32);
	v_lshlrev_b32_e32 v229, 16, v112
	v_and_b32_e32 v230, 0xffff0000, v112
	v_mul_f32_e32 v232, v229, v229
	v_fmac_f32_e32 v232, v230, v230
	v_lshlrev_b32_e32 v229, 16, v113
	v_and_b32_e32 v230, 0xffff0000, v113
	v_fmac_f32_e32 v232, v229, v229
	v_fmac_f32_e32 v232, v230, v230
	v_lshlrev_b32_e32 v229, 16, v114
	v_and_b32_e32 v230, 0xffff0000, v114
	v_fmac_f32_e32 v232, v229, v229
	v_fmac_f32_e32 v232, v230, v230
	v_lshlrev_b32_e32 v229, 16, v115
	v_and_b32_e32 v230, 0xffff0000, v115
	v_fmac_f32_e32 v232, v229, v229
	v_fmac_f32_e32 v232, v230, v230
	v_lshlrev_b32_e32 v229, 16, v116
	v_and_b32_e32 v230, 0xffff0000, v116
	v_fmac_f32_e32 v232, v229, v229
	v_fmac_f32_e32 v232, v230, v230
	v_lshlrev_b32_e32 v229, 16, v117
	v_and_b32_e32 v230, 0xffff0000, v117
	v_fmac_f32_e32 v232, v229, v229
	v_fmac_f32_e32 v232, v230, v230
	v_lshlrev_b32_e32 v229, 16, v118
	v_and_b32_e32 v230, 0xffff0000, v118
	v_fmac_f32_e32 v232, v229, v229
	v_fmac_f32_e32 v232, v230, v230
	v_lshlrev_b32_e32 v229, 16, v119
	v_and_b32_e32 v230, 0xffff0000, v119
	v_fmac_f32_e32 v232, v229, v229
	v_fmac_f32_e32 v232, v230, v230
	v_lshlrev_b32_e32 v229, 16, v120
	v_and_b32_e32 v230, 0xffff0000, v120
	v_fmac_f32_e32 v232, v229, v229
	v_fmac_f32_e32 v232, v230, v230
	v_lshlrev_b32_e32 v229, 16, v121
	v_and_b32_e32 v230, 0xffff0000, v121
	v_fmac_f32_e32 v232, v229, v229
	v_fmac_f32_e32 v232, v230, v230
	v_lshlrev_b32_e32 v229, 16, v122
	v_and_b32_e32 v230, 0xffff0000, v122
	v_fmac_f32_e32 v232, v229, v229
	v_fmac_f32_e32 v232, v230, v230
	v_lshlrev_b32_e32 v229, 16, v123
	v_and_b32_e32 v230, 0xffff0000, v123
	v_fmac_f32_e32 v232, v229, v229
	v_fmac_f32_e32 v232, v230, v230
	v_lshlrev_b32_e32 v229, 16, v124
	v_and_b32_e32 v230, 0xffff0000, v124
	v_fmac_f32_e32 v232, v229, v229
	v_fmac_f32_e32 v232, v230, v230
	v_lshlrev_b32_e32 v229, 16, v125
	v_and_b32_e32 v230, 0xffff0000, v125
	v_fmac_f32_e32 v232, v229, v229
	v_fmac_f32_e32 v232, v230, v230
	v_lshlrev_b32_e32 v229, 16, v126
	v_and_b32_e32 v230, 0xffff0000, v126
	v_fmac_f32_e32 v232, v229, v229
	v_fmac_f32_e32 v232, v230, v230
	v_lshlrev_b32_e32 v229, 16, v127
	v_and_b32_e32 v230, 0xffff0000, v127
	v_fmac_f32_e32 v232, v229, v229
	v_fmac_f32_e32 v232, v230, v230
	v_lshlrev_b32_e32 v229, 16, v128
	v_and_b32_e32 v230, 0xffff0000, v128
	v_fmac_f32_e32 v232, v229, v229
	v_fmac_f32_e32 v232, v230, v230
	v_lshlrev_b32_e32 v229, 16, v129
	v_and_b32_e32 v230, 0xffff0000, v129
	v_fmac_f32_e32 v232, v229, v229
	v_fmac_f32_e32 v232, v230, v230
	v_lshlrev_b32_e32 v229, 16, v130
	v_and_b32_e32 v230, 0xffff0000, v130
	v_fmac_f32_e32 v232, v229, v229
	v_fmac_f32_e32 v232, v230, v230
	v_lshlrev_b32_e32 v229, 16, v131
	v_and_b32_e32 v230, 0xffff0000, v131
	v_fmac_f32_e32 v232, v229, v229
	v_fmac_f32_e32 v232, v230, v230
	v_lshlrev_b32_e32 v229, 16, v132
	v_and_b32_e32 v230, 0xffff0000, v132
	v_fmac_f32_e32 v232, v229, v229
	v_fmac_f32_e32 v232, v230, v230
	v_lshlrev_b32_e32 v229, 16, v133
	v_and_b32_e32 v230, 0xffff0000, v133
	v_fmac_f32_e32 v232, v229, v229
	v_fmac_f32_e32 v232, v230, v230
	v_lshlrev_b32_e32 v229, 16, v134
	v_and_b32_e32 v230, 0xffff0000, v134
	v_fmac_f32_e32 v232, v229, v229
	v_fmac_f32_e32 v232, v230, v230
	v_lshlrev_b32_e32 v229, 16, v135
	v_and_b32_e32 v230, 0xffff0000, v135
	v_fmac_f32_e32 v232, v229, v229
	v_fmac_f32_e32 v232, v230, v230
	v_lshlrev_b32_e32 v229, 16, v136
	v_and_b32_e32 v230, 0xffff0000, v136
	v_fmac_f32_e32 v232, v229, v229
	v_fmac_f32_e32 v232, v230, v230
	v_lshlrev_b32_e32 v229, 16, v137
	v_and_b32_e32 v230, 0xffff0000, v137
	v_fmac_f32_e32 v232, v229, v229
	v_fmac_f32_e32 v232, v230, v230
	v_lshlrev_b32_e32 v229, 16, v138
	v_and_b32_e32 v230, 0xffff0000, v138
	v_fmac_f32_e32 v232, v229, v229
	v_fmac_f32_e32 v232, v230, v230
	v_lshlrev_b32_e32 v229, 16, v139
	v_and_b32_e32 v230, 0xffff0000, v139
	v_fmac_f32_e32 v232, v229, v229
	v_fmac_f32_e32 v232, v230, v230
	v_lshlrev_b32_e32 v229, 16, v140
	v_and_b32_e32 v230, 0xffff0000, v140
	v_fmac_f32_e32 v232, v229, v229
	v_fmac_f32_e32 v232, v230, v230
	v_lshlrev_b32_e32 v229, 16, v141
	v_and_b32_e32 v230, 0xffff0000, v141
	v_fmac_f32_e32 v232, v229, v229
	v_fmac_f32_e32 v232, v230, v230
	v_lshlrev_b32_e32 v229, 16, v142
	v_and_b32_e32 v230, 0xffff0000, v142
	v_fmac_f32_e32 v232, v229, v229
	v_fmac_f32_e32 v232, v230, v230
	v_lshlrev_b32_e32 v229, 16, v143
	v_and_b32_e32 v230, 0xffff0000, v143
	v_fmac_f32_e32 v232, v229, v229
	v_fmac_f32_e32 v232, v230, v230
	v_lshlrev_b32_e32 v229, 16, v144
	v_and_b32_e32 v230, 0xffff0000, v144
	v_mul_f32_e32 v233, v229, v229
	v_fmac_f32_e32 v233, v230, v230
	v_lshlrev_b32_e32 v229, 16, v145
	v_and_b32_e32 v230, 0xffff0000, v145
	v_fmac_f32_e32 v233, v229, v229
	v_fmac_f32_e32 v233, v230, v230
	v_lshlrev_b32_e32 v229, 16, v146
	v_and_b32_e32 v230, 0xffff0000, v146
	v_fmac_f32_e32 v233, v229, v229
	v_fmac_f32_e32 v233, v230, v230
	v_lshlrev_b32_e32 v229, 16, v147
	v_and_b32_e32 v230, 0xffff0000, v147
	v_fmac_f32_e32 v233, v229, v229
	v_fmac_f32_e32 v233, v230, v230
	v_lshlrev_b32_e32 v229, 16, v148
	v_and_b32_e32 v230, 0xffff0000, v148
	v_fmac_f32_e32 v233, v229, v229
	v_fmac_f32_e32 v233, v230, v230
	v_lshlrev_b32_e32 v229, 16, v149
	v_and_b32_e32 v230, 0xffff0000, v149
	v_fmac_f32_e32 v233, v229, v229
	v_fmac_f32_e32 v233, v230, v230
	v_lshlrev_b32_e32 v229, 16, v150
	v_and_b32_e32 v230, 0xffff0000, v150
	v_fmac_f32_e32 v233, v229, v229
	v_fmac_f32_e32 v233, v230, v230
	v_lshlrev_b32_e32 v229, 16, v151
	v_and_b32_e32 v230, 0xffff0000, v151
	v_fmac_f32_e32 v233, v229, v229
	v_fmac_f32_e32 v233, v230, v230
	v_lshlrev_b32_e32 v229, 16, v152
	v_and_b32_e32 v230, 0xffff0000, v152
	v_fmac_f32_e32 v233, v229, v229
	v_fmac_f32_e32 v233, v230, v230
; DI u32x4 pack8(const float (&f)[8]) { u32x4 w; w.x = pk2(f[0], f[1]); w.y = pk2(f[2], f[3]); w.z = pk2(f[4], f[5]); w.w = pk2(f[6], f[7]); return w; }
; template <int DQK, int KA8, int DV, bool BIAS, bool JOINT>
; DI void attn_core(LAS unsigned char* lds, const bf16_t* Qrow, const bf16_t* KpA, int ldkA, const bf16_t* KpB, int ldkB, const bf16_t* Vp, int ldv,
;                   int qb, int wid, int lane, const float* qng  , f32x16 (&O)[DV / 32]) {
;     ...
;             ssn += __shfl_xor(ssn, 32); ssr += __shfl_xor(ssr, 32);
;             const float qs = 0.07216878364870322f * LOG2E, scn = rsqrtf(ssn * (1.f / 128.f) + EPS) * qs, scr = rsqrtf(ssr * (1.f / 64.f) + EPS) * qs;
; #pragma unroll
;             for (int s = 0; s < 8; ++s) { float f[8]; unpack8(__builtin_bit_cast(u32x4, qf[s]), f);
;                 const f32x4 g0 = *(const f32x4*)(qng + 16 * s + 8 * hh), g1 = *(const f32x4*)(qng + 16 * s + 8 * hh + 4);
; #pragma unroll
;                 for (int e = 0; e < 4; ++e) { f[e] *= scn * g0[e]; f[4 + e] *= scn * g1[e]; }
;                 qf[s] = __builtin_bit_cast(bf16x8, pack8(f)); }
	v_lshlrev_b32_e32 v229, 16, v153
	v_and_b32_e32 v230, 0xffff0000, v153
	v_fmac_f32_e32 v233, v229, v229
	v_fmac_f32_e32 v233, v230, v230
	v_lshlrev_b32_e32 v229, 16, v154
	v_and_b32_e32 v230, 0xffff0000, v154
	v_fmac_f32_e32 v233, v229, v229
	v_fmac_f32_e32 v233, v230, v230
	v_lshlrev_b32_e32 v229, 16, v155
	v_and_b32_e32 v230, 0xffff0000, v155
	v_fmac_f32_e32 v233, v229, v229
	v_fmac_f32_e32 v233, v230, v230
	v_lshlrev_b32_e32 v229, 16, v156
	v_and_b32_e32 v230, 0xffff0000, v156
	v_fmac_f32_e32 v233, v229, v229
	v_fmac_f32_e32 v233, v230, v230
	v_lshlrev_b32_e32 v229, 16, v157
	v_and_b32_e32 v230, 0xffff0000, v157
	v_fmac_f32_e32 v233, v229, v229
	v_fmac_f32_e32 v233, v230, v230
	v_lshlrev_b32_e32 v229, 16, v158
	v_and_b32_e32 v230, 0xffff0000, v158
	v_fmac_f32_e32 v233, v229, v229
	v_fmac_f32_e32 v233, v230, v230
	v_lshlrev_b32_e32 v229, 16, v159
	v_and_b32_e32 v230, 0xffff0000, v159
	v_fmac_f32_e32 v233, v229, v229
	v_fmac_f32_e32 v233, v230, v230
	v_mov_b32_e32 v230, v232
	v_mov_b32_e32 v231, v232
	s_nop 1
	v_permlane32_swap_b32_e32 v230, v231
	s_nop 1
	v_add_f32_e32 v232, v230, v231
	v_mov_b32_e32 v230, v233
	v_mov_b32_e32 v231, v233
	s_nop 1
	v_permlane32_swap_b32_e32 v230, v231
	s_nop 1
	v_add_f32_e32 v233, v230, v231
	v_mul_f32_e32 v232, 0x3c000000, v232
	v_mul_f32_e32 v233, 0x3c800000, v233
	v_add_f32_e32 v232, 0x358637bd, v232
	v_add_f32_e32 v233, 0x358637bd, v233
	v_rsq_f32_e32 v232, v232
	v_rsq_f32_e32 v233, v233
	s_nop 1
	v_mul_f32_e32 v241, 0x3dd53b95, v232
	v_mul_f32_e32 v242, 0x3dd53b95, v233
	ds_read_b128 v[182:185], v239 offset:0
	ds_read_b128 v[186:189], v239 offset:16
	s_waitcnt lgkmcnt(0)
	v_lshlrev_b32_e32 v229, 16, v112
	v_and_b32_e32 v230, 0xffff0000, v112
	v_mul_f32_e32 v234, v241, v182
	v_mul_f32_e32 v235, v241, v183
	v_mul_f32_e32 v229, v229, v234
	v_mul_f32_e32 v230, v230, v235
	v_cvt_pk_bf16_f32 v112, v229, v230
	v_lshlrev_b32_e32 v229, 16, v113
	v_and_b32_e32 v230, 0xffff0000, v113
	v_mul_f32_e32 v234, v241, v184
	v_mul_f32_e32 v235, v241, v185
	v_mul_f32_e32 v229, v229, v234
	v_mul_f32_e32 v230, v230, v235
	v_cvt_pk_bf16_f32 v113, v229, v230
	v_lshlrev_b32_e32 v229, 16, v114
	v_and_b32_e32 v230, 0xffff0000, v114
	v_mul_f32_e32 v234, v241, v186
	v_mul_f32_e32 v235, v241, v187
	v_mul_f32_e32 v229, v229, v234
	v_mul_f32_e32 v230, v230, v235
	v_cvt_pk_bf16_f32 v114, v229, v230
	v_lshlrev_b32_e32 v229, 16, v115
	v_and_b32_e32 v230, 0xffff0000, v115
	v_mul_f32_e32 v234, v241, v188
	v_mul_f32_e32 v235, v241, v189
	v_mul_f32_e32 v229, v229, v234
	v_mul_f32_e32 v230, v230, v235
	v_cvt_pk_bf16_f32 v115, v229, v230
	ds_read_b128 v[182:185], v239 offset:64
	ds_read_b128 v[186:189], v239 offset:80
	s_waitcnt lgkmcnt(0)
	v_lshlrev_b32_e32 v229, 16, v116
	v_and_b32_e32 v230, 0xffff0000, v116
	v_mul_f32_e32 v234, v241, v182
	v_mul_f32_e32 v235, v241, v183
	v_mul_f32_e32 v229, v229, v234
	v_mul_f32_e32 v230, v230, v235
	v_cvt_pk_bf16_f32 v116, v229, v230
	v_lshlrev_b32_e32 v229, 16, v117
	v_and_b32_e32 v230, 0xffff0000, v117
	v_mul_f32_e32 v234, v241, v184
	v_mul_f32_e32 v235, v241, v185
	v_mul_f32_e32 v229, v229, v234
	v_mul_f32_e32 v230, v230, v235
	v_cvt_pk_bf16_f32 v117, v229, v230
	v_lshlrev_b32_e32 v229, 16, v118
	v_and_b32_e32 v230, 0xffff0000, v118
	v_mul_f32_e32 v234, v241, v186
	v_mul_f32_e32 v235, v241, v187
	v_mul_f32_e32 v229, v229, v234
	v_mul_f32_e32 v230, v230, v235
	v_cvt_pk_bf16_f32 v118, v229, v230
	v_lshlrev_b32_e32 v229, 16, v119
	v_and_b32_e32 v230, 0xffff0000, v119
	v_mul_f32_e32 v234, v241, v188
	v_mul_f32_e32 v235, v241, v189
	v_mul_f32_e32 v229, v229, v234
	v_mul_f32_e32 v230, v230, v235
	v_cvt_pk_bf16_f32 v119, v229, v230
	ds_read_b128 v[182:185], v239 offset:128
	ds_read_b128 v[186:189], v239 offset:144
	s_waitcnt lgkmcnt(0)
	v_lshlrev_b32_e32 v229, 16, v120
	v_and_b32_e32 v230, 0xffff0000, v120
	v_mul_f32_e32 v234, v241, v182
	v_mul_f32_e32 v235, v241, v183
	v_mul_f32_e32 v229, v229, v234
	v_mul_f32_e32 v230, v230, v235
	v_cvt_pk_bf16_f32 v120, v229, v230
	v_lshlrev_b32_e32 v229, 16, v121
	v_and_b32_e32 v230, 0xffff0000, v121
	v_mul_f32_e32 v234, v241, v184
	v_mul_f32_e32 v235, v241, v185
	v_mul_f32_e32 v229, v229, v234
	v_mul_f32_e32 v230, v230, v235
	v_cvt_pk_bf16_f32 v121, v229, v230
	v_lshlrev_b32_e32 v229, 16, v122
	v_and_b32_e32 v230, 0xffff0000, v122
	v_mul_f32_e32 v234, v241, v186
	v_mul_f32_e32 v235, v241, v187
	v_mul_f32_e32 v229, v229, v234
	v_mul_f32_e32 v230, v230, v235
	v_cvt_pk_bf16_f32 v122, v229, v230
	v_lshlrev_b32_e32 v229, 16, v123
	v_and_b32_e32 v230, 0xffff0000, v123
	v_mul_f32_e32 v234, v241, v188
	v_mul_f32_e32 v235, v241, v189
	v_mul_f32_e32 v229, v229, v234
	v_mul_f32_e32 v230, v230, v235
	v_cvt_pk_bf16_f32 v123, v229, v230
	ds_read_b128 v[182:185], v239 offset:192
	ds_read_b128 v[186:189], v239 offset:208
	s_waitcnt lgkmcnt(0)
	v_lshlrev_b32_e32 v229, 16, v124
	v_and_b32_e32 v230, 0xffff0000, v124
	v_mul_f32_e32 v234, v241, v182
	v_mul_f32_e32 v235, v241, v183
	v_mul_f32_e32 v229, v229, v234
	v_mul_f32_e32 v230, v230, v235
	v_cvt_pk_bf16_f32 v124, v229, v230
	v_lshlrev_b32_e32 v229, 16, v125
	v_and_b32_e32 v230, 0xffff0000, v125
	v_mul_f32_e32 v234, v241, v184
	v_mul_f32_e32 v235, v241, v185
	v_mul_f32_e32 v229, v229, v234
	v_mul_f32_e32 v230, v230, v235
	v_cvt_pk_bf16_f32 v125, v229, v230
	v_lshlrev_b32_e32 v229, 16, v126
	v_and_b32_e32 v230, 0xffff0000, v126
	v_mul_f32_e32 v234, v241, v186
	v_mul_f32_e32 v235, v241, v187
	v_mul_f32_e32 v229, v229, v234
	v_mul_f32_e32 v230, v230, v235
	v_cvt_pk_bf16_f32 v126, v229, v230
	v_lshlrev_b32_e32 v229, 16, v127
	v_and_b32_e32 v230, 0xffff0000, v127
	v_mul_f32_e32 v234, v241, v188
	v_mul_f32_e32 v235, v241, v189
	v_mul_f32_e32 v229, v229, v234
	v_mul_f32_e32 v230, v230, v235
	v_cvt_pk_bf16_f32 v127, v229, v230
	ds_read_b128 v[182:185], v239 offset:256
	ds_read_b128 v[186:189], v239 offset:272
	s_waitcnt lgkmcnt(0)
; DI u32x4 pack8(const float (&f)[8]) { u32x4 w; w.x = pk2(f[0], f[1]); w.y = pk2(f[2], f[3]); w.z = pk2(f[4], f[5]); w.w = pk2(f[6], f[7]); return w; }
; template <int DQK, int KA8, int DV, bool BIAS, bool JOINT>
; DI void attn_core(LAS unsigned char* lds, const bf16_t* Qrow, const bf16_t* KpA, int ldkA, const bf16_t* KpB, int ldkB, const bf16_t* Vp, int ldv,
;                   int qb, int wid, int lane, const float* qng  , f32x16 (&O)[DV / 32]) {
;     ...
;             for (int s = 0; s < 8; ++s) { float f[8]; unpack8(__builtin_bit_cast(u32x4, qf[s]), f);
;                 const f32x4 g0 = *(const f32x4*)(qng + 16 * s + 8 * hh), g1 = *(const f32x4*)(qng + 16 * s + 8 * hh + 4);
; #pragma unroll
;                 for (int e = 0; e < 4; ++e) { f[e] *= scn * g0[e]; f[4 + e] *= scn * g1[e]; }
;                 qf[s] = __builtin_bit_cast(bf16x8, pack8(f)); }
;     ...
;                     const float a1 = f1[e] * scr * qng[128 + i], a2 = f2[e] * scr * qng[160 + i];
	v_lshlrev_b32_e32 v229, 16, v128
	v_and_b32_e32 v230, 0xffff0000, v128
	v_mul_f32_e32 v234, v241, v182
	v_mul_f32_e32 v235, v241, v183
	v_mul_f32_e32 v229, v229, v234
	v_mul_f32_e32 v230, v230, v235
	v_cvt_pk_bf16_f32 v128, v229, v230
	v_lshlrev_b32_e32 v229, 16, v129
	v_and_b32_e32 v230, 0xffff0000, v129
	v_mul_f32_e32 v234, v241, v184
	v_mul_f32_e32 v235, v241, v185
	v_mul_f32_e32 v229, v229, v234
	v_mul_f32_e32 v230, v230, v235
	v_cvt_pk_bf16_f32 v129, v229, v230
	v_lshlrev_b32_e32 v229, 16, v130
	v_and_b32_e32 v230, 0xffff0000, v130
	v_mul_f32_e32 v234, v241, v186
	v_mul_f32_e32 v235, v241, v187
	v_mul_f32_e32 v229, v229, v234
	v_mul_f32_e32 v230, v230, v235
	v_cvt_pk_bf16_f32 v130, v229, v230
	v_lshlrev_b32_e32 v229, 16, v131
	v_and_b32_e32 v230, 0xffff0000, v131
	v_mul_f32_e32 v234, v241, v188
	v_mul_f32_e32 v235, v241, v189
	v_mul_f32_e32 v229, v229, v234
	v_mul_f32_e32 v230, v230, v235
	v_cvt_pk_bf16_f32 v131, v229, v230
	ds_read_b128 v[182:185], v239 offset:320
	ds_read_b128 v[186:189], v239 offset:336
	s_waitcnt lgkmcnt(0)
	v_lshlrev_b32_e32 v229, 16, v132
	v_and_b32_e32 v230, 0xffff0000, v132
	v_mul_f32_e32 v234, v241, v182
	v_mul_f32_e32 v235, v241, v183
	v_mul_f32_e32 v229, v229, v234
	v_mul_f32_e32 v230, v230, v235
	v_cvt_pk_bf16_f32 v132, v229, v230
	v_lshlrev_b32_e32 v229, 16, v133
	v_and_b32_e32 v230, 0xffff0000, v133
	v_mul_f32_e32 v234, v241, v184
	v_mul_f32_e32 v235, v241, v185
	v_mul_f32_e32 v229, v229, v234
	v_mul_f32_e32 v230, v230, v235
	v_cvt_pk_bf16_f32 v133, v229, v230
	v_lshlrev_b32_e32 v229, 16, v134
	v_and_b32_e32 v230, 0xffff0000, v134
	v_mul_f32_e32 v234, v241, v186
	v_mul_f32_e32 v235, v241, v187
	v_mul_f32_e32 v229, v229, v234
	v_mul_f32_e32 v230, v230, v235
	v_cvt_pk_bf16_f32 v134, v229, v230
	v_lshlrev_b32_e32 v229, 16, v135
	v_and_b32_e32 v230, 0xffff0000, v135
	v_mul_f32_e32 v234, v241, v188
	v_mul_f32_e32 v235, v241, v189
	v_mul_f32_e32 v229, v229, v234
	v_mul_f32_e32 v230, v230, v235
	v_cvt_pk_bf16_f32 v135, v229, v230
	ds_read_b128 v[182:185], v239 offset:384
	ds_read_b128 v[186:189], v239 offset:400
	s_waitcnt lgkmcnt(0)
	v_lshlrev_b32_e32 v229, 16, v136
	v_and_b32_e32 v230, 0xffff0000, v136
	v_mul_f32_e32 v234, v241, v182
	v_mul_f32_e32 v235, v241, v183
	v_mul_f32_e32 v229, v229, v234
	v_mul_f32_e32 v230, v230, v235
	v_cvt_pk_bf16_f32 v136, v229, v230
	v_lshlrev_b32_e32 v229, 16, v137
	v_and_b32_e32 v230, 0xffff0000, v137
	v_mul_f32_e32 v234, v241, v184
	v_mul_f32_e32 v235, v241, v185
	v_mul_f32_e32 v229, v229, v234
	v_mul_f32_e32 v230, v230, v235
	v_cvt_pk_bf16_f32 v137, v229, v230
	v_lshlrev_b32_e32 v229, 16, v138
	v_and_b32_e32 v230, 0xffff0000, v138
	v_mul_f32_e32 v234, v241, v186
	v_mul_f32_e32 v235, v241, v187
	v_mul_f32_e32 v229, v229, v234
	v_mul_f32_e32 v230, v230, v235
	v_cvt_pk_bf16_f32 v138, v229, v230
	v_lshlrev_b32_e32 v229, 16, v139
	v_and_b32_e32 v230, 0xffff0000, v139
	v_mul_f32_e32 v234, v241, v188
	v_mul_f32_e32 v235, v241, v189
	v_mul_f32_e32 v229, v229, v234
	v_mul_f32_e32 v230, v230, v235
	v_cvt_pk_bf16_f32 v139, v229, v230
	ds_read_b128 v[182:185], v239 offset:448
	ds_read_b128 v[186:189], v239 offset:464
	s_waitcnt lgkmcnt(0)
	v_lshlrev_b32_e32 v229, 16, v140
	v_and_b32_e32 v230, 0xffff0000, v140
	v_mul_f32_e32 v234, v241, v182
	v_mul_f32_e32 v235, v241, v183
	v_mul_f32_e32 v229, v229, v234
	v_mul_f32_e32 v230, v230, v235
	v_cvt_pk_bf16_f32 v140, v229, v230
	v_lshlrev_b32_e32 v229, 16, v141
	v_and_b32_e32 v230, 0xffff0000, v141
	v_mul_f32_e32 v234, v241, v184
	v_mul_f32_e32 v235, v241, v185
	v_mul_f32_e32 v229, v229, v234
	v_mul_f32_e32 v230, v230, v235
	v_cvt_pk_bf16_f32 v141, v229, v230
	v_lshlrev_b32_e32 v229, 16, v142
	v_and_b32_e32 v230, 0xffff0000, v142
	v_mul_f32_e32 v234, v241, v186
	v_mul_f32_e32 v235, v241, v187
	v_mul_f32_e32 v229, v229, v234
	v_mul_f32_e32 v230, v230, v235
	v_cvt_pk_bf16_f32 v142, v229, v230
	v_lshlrev_b32_e32 v229, 16, v143
	v_and_b32_e32 v230, 0xffff0000, v143
	v_mul_f32_e32 v234, v241, v188
	v_mul_f32_e32 v235, v241, v189
	v_mul_f32_e32 v229, v229, v234
	v_mul_f32_e32 v230, v230, v235
	v_cvt_pk_bf16_f32 v143, v229, v230
	ds_read_b128 v[182:185], v239 offset:512
	ds_read_b128 v[186:189], v239 offset:528
	ds_read_b128 v[190:193], v239 offset:640
	ds_read_b128 v[194:197], v239 offset:656
	s_waitcnt lgkmcnt(0)
; DI u32x4 pack8(const float (&f)[8]) { u32x4 w; w.x = pk2(f[0], f[1]); w.y = pk2(f[2], f[3]); w.z = pk2(f[4], f[5]); w.w = pk2(f[6], f[7]); return w; }
; template <int DQK, int KA8, int DV, bool BIAS, bool JOINT>
; DI void attn_core(LAS unsigned char* lds, const bf16_t* Qrow, const bf16_t* KpA, int ldkA, const bf16_t* KpB, int ldkB, const bf16_t* Vp, int ldv,
;                   int qb, int wid, int lane, const float* qng  , f32x16 (&O)[DV / 32]) {
;     ...
;             const float posr = (float)(qb * 256 + wid * 32 + l32) * 0.15915494309189535f;
; #pragma unroll
;             for (int s = 8; s < 10; ++s) { float f1[8], f2[8]; unpack8(__builtin_bit_cast(u32x4, qf[s]), f1); unpack8(__builtin_bit_cast(u32x4, qf[s + 2]), f2);
; #pragma unroll
;                 for (int e = 0; e < 8; ++e) { const int i = 16 * (s - 8) + 8 * hh + e;
;                     const float a1 = f1[e] * scr * qng[128 + i], a2 = f2[e] * scr * qng[160 + i];
;                     float rev = posr * __builtin_amdgcn_exp2f(-(float)i * 0.41524101186092029f); rev -= floorf(rev);
;                     const float sn = __builtin_amdgcn_sinf(rev), cs = __builtin_amdgcn_cosf(rev);
;                     f1[e] = a1 * cs - a2 * sn; f2[e] = a2 * cs + a1 * sn; }
;                 qf[s] = __builtin_bit_cast(bf16x8, pack8(f1)); qf[s + 2] = __builtin_bit_cast(bf16x8, pack8(f2)); }
	v_lshl_add_u32 v229, v227, 3, 0
	v_cvt_f32_u32_e32 v229, v229
	v_mul_f32_e32 v229, 0xbed49a78, v229
	v_exp_f32_e32 v229, v229
	v_lshlrev_b32_e32 v234, 16, v144
	v_lshlrev_b32_e32 v235, 16, v152
	v_mul_f32_e32 v229, v240, v229
	v_mul_f32_e32 v234, v234, v242
	v_mul_f32_e32 v235, v235, v242
	v_fract_f32_e32 v229, v229
	v_mul_f32_e32 v234, v234, v182
	v_mul_f32_e32 v235, v235, v190
	v_sin_f32_e32 v230, v229
	v_cos_f32_e32 v231, v229
	s_nop 1
	v_mul_f32_e32 v236, v235, v230
	v_mul_f32_e32 v233, v234, v230
	v_fma_f32 v243, v234, v231, -v236
	v_fma_f32 v245, v235, v231, v233
	v_lshl_add_u32 v229, v227, 3, 1
	v_cvt_f32_u32_e32 v229, v229
	v_mul_f32_e32 v229, 0xbed49a78, v229
	v_exp_f32_e32 v229, v229
	v_and_b32_e32 v234, 0xffff0000, v144
	v_and_b32_e32 v235, 0xffff0000, v152
	v_mul_f32_e32 v229, v240, v229
	v_mul_f32_e32 v234, v234, v242
	v_mul_f32_e32 v235, v235, v242
	v_fract_f32_e32 v229, v229
	v_mul_f32_e32 v234, v234, v183
	v_mul_f32_e32 v235, v235, v191
	v_sin_f32_e32 v230, v229
	v_cos_f32_e32 v231, v229
	s_nop 1
	v_mul_f32_e32 v236, v235, v230
	v_mul_f32_e32 v233, v234, v230
	v_fma_f32 v244, v234, v231, -v236
	v_fma_f32 v246, v235, v231, v233
	v_cvt_pk_bf16_f32 v144, v243, v244
	v_cvt_pk_bf16_f32 v152, v245, v246
	v_lshl_add_u32 v229, v227, 3, 2
	v_cvt_f32_u32_e32 v229, v229
	v_mul_f32_e32 v229, 0xbed49a78, v229
	v_exp_f32_e32 v229, v229
	v_lshlrev_b32_e32 v234, 16, v145
	v_lshlrev_b32_e32 v235, 16, v153
	v_mul_f32_e32 v229, v240, v229
	v_mul_f32_e32 v234, v234, v242
	v_mul_f32_e32 v235, v235, v242
	v_fract_f32_e32 v229, v229
	v_mul_f32_e32 v234, v234, v184
	v_mul_f32_e32 v235, v235, v192
	v_sin_f32_e32 v230, v229
	v_cos_f32_e32 v231, v229
	s_nop 1
	v_mul_f32_e32 v236, v235, v230
	v_mul_f32_e32 v233, v234, v230
	v_fma_f32 v243, v234, v231, -v236
	v_fma_f32 v245, v235, v231, v233
	v_lshl_add_u32 v229, v227, 3, 3
	v_cvt_f32_u32_e32 v229, v229
	v_mul_f32_e32 v229, 0xbed49a78, v229
	v_exp_f32_e32 v229, v229
	v_and_b32_e32 v234, 0xffff0000, v145
	v_and_b32_e32 v235, 0xffff0000, v153
	v_mul_f32_e32 v229, v240, v229
	v_mul_f32_e32 v234, v234, v242
	v_mul_f32_e32 v235, v235, v242
	v_fract_f32_e32 v229, v229
	v_mul_f32_e32 v234, v234, v185
	v_mul_f32_e32 v235, v235, v193
	v_sin_f32_e32 v230, v229
	v_cos_f32_e32 v231, v229
	s_nop 1
	v_mul_f32_e32 v236, v235, v230
	v_mul_f32_e32 v233, v234, v230
	v_fma_f32 v244, v234, v231, -v236
	v_fma_f32 v246, v235, v231, v233
	v_cvt_pk_bf16_f32 v145, v243, v244
	v_cvt_pk_bf16_f32 v153, v245, v246
	v_lshl_add_u32 v229, v227, 3, 4
	v_cvt_f32_u32_e32 v229, v229
	v_mul_f32_e32 v229, 0xbed49a78, v229
	v_exp_f32_e32 v229, v229
	v_lshlrev_b32_e32 v234, 16, v146
	v_lshlrev_b32_e32 v235, 16, v154
	v_mul_f32_e32 v229, v240, v229
	v_mul_f32_e32 v234, v234, v242
	v_mul_f32_e32 v235, v235, v242
	v_fract_f32_e32 v229, v229
	v_mul_f32_e32 v234, v234, v186
	v_mul_f32_e32 v235, v235, v194
	v_sin_f32_e32 v230, v229
	v_cos_f32_e32 v231, v229
	s_nop 1
	v_mul_f32_e32 v236, v235, v230
	v_mul_f32_e32 v233, v234, v230
	v_fma_f32 v243, v234, v231, -v236
	v_fma_f32 v245, v235, v231, v233
	v_lshl_add_u32 v229, v227, 3, 5
	v_cvt_f32_u32_e32 v229, v229
	v_mul_f32_e32 v229, 0xbed49a78, v229
	v_exp_f32_e32 v229, v229
	v_and_b32_e32 v234, 0xffff0000, v146
	v_and_b32_e32 v235, 0xffff0000, v154
	v_mul_f32_e32 v229, v240, v229
	v_mul_f32_e32 v234, v234, v242
	v_mul_f32_e32 v235, v235, v242
	v_fract_f32_e32 v229, v229
	v_mul_f32_e32 v234, v234, v187
	v_mul_f32_e32 v235, v235, v195
	v_sin_f32_e32 v230, v229
	v_cos_f32_e32 v231, v229
	s_nop 1
	v_mul_f32_e32 v236, v235, v230
	v_mul_f32_e32 v233, v234, v230
	v_fma_f32 v244, v234, v231, -v236
	v_fma_f32 v246, v235, v231, v233
	v_cvt_pk_bf16_f32 v146, v243, v244
	v_cvt_pk_bf16_f32 v154, v245, v246
	v_lshl_add_u32 v229, v227, 3, 6
	v_cvt_f32_u32_e32 v229, v229
	v_mul_f32_e32 v229, 0xbed49a78, v229
	v_exp_f32_e32 v229, v229
	v_lshlrev_b32_e32 v234, 16, v147
	v_lshlrev_b32_e32 v235, 16, v155
	v_mul_f32_e32 v229, v240, v229
	v_mul_f32_e32 v234, v234, v242
	v_mul_f32_e32 v235, v235, v242
	v_fract_f32_e32 v229, v229
	v_mul_f32_e32 v234, v234, v188
	v_mul_f32_e32 v235, v235, v196
	v_sin_f32_e32 v230, v229
	v_cos_f32_e32 v231, v229
	s_nop 1
	v_mul_f32_e32 v236, v235, v230
	v_mul_f32_e32 v233, v234, v230
	v_fma_f32 v243, v234, v231, -v236
	v_fma_f32 v245, v235, v231, v233
	v_lshl_add_u32 v229, v227, 3, 7
	v_cvt_f32_u32_e32 v229, v229
	v_mul_f32_e32 v229, 0xbed49a78, v229
	v_exp_f32_e32 v229, v229
	v_and_b32_e32 v234, 0xffff0000, v147
	v_and_b32_e32 v235, 0xffff0000, v155
	v_mul_f32_e32 v229, v240, v229
	v_mul_f32_e32 v234, v234, v242
	v_mul_f32_e32 v235, v235, v242
	v_fract_f32_e32 v229, v229
	v_mul_f32_e32 v234, v234, v189
	v_mul_f32_e32 v235, v235, v197
	v_sin_f32_e32 v230, v229
	v_cos_f32_e32 v231, v229
	s_nop 1
	v_mul_f32_e32 v236, v235, v230
	v_mul_f32_e32 v233, v234, v230
	v_fma_f32 v244, v234, v231, -v236
	v_fma_f32 v246, v235, v231, v233
	v_cvt_pk_bf16_f32 v147, v243, v244
	v_cvt_pk_bf16_f32 v155, v245, v246
	ds_read_b128 v[182:185], v239 offset:576
	ds_read_b128 v[186:189], v239 offset:592
	ds_read_b128 v[190:193], v239 offset:704
	ds_read_b128 v[194:197], v239 offset:720
	s_waitcnt lgkmcnt(0)
; DI u32x4 pack8(const float (&f)[8]) { u32x4 w; w.x = pk2(f[0], f[1]); w.y = pk2(f[2], f[3]); w.z = pk2(f[4], f[5]); w.w = pk2(f[6], f[7]); return w; }
; template <int DQK, int KA8, int DV, bool BIAS, bool JOINT>
; DI void attn_core(LAS unsigned char* lds, const bf16_t* Qrow, const bf16_t* KpA, int ldkA, const bf16_t* KpB, int ldkB, const bf16_t* Vp, int ldv,
;                   int qb, int wid, int lane, const float* qng  , f32x16 (&O)[DV / 32]) {
;     ...
; #pragma unroll
;             for (int s = 8; s < 10; ++s) { float f1[8], f2[8]; unpack8(__builtin_bit_cast(u32x4, qf[s]), f1); unpack8(__builtin_bit_cast(u32x4, qf[s + 2]), f2);
; #pragma unroll
;                 for (int e = 0; e < 8; ++e) { const int i = 16 * (s - 8) + 8 * hh + e;
;                     const float a1 = f1[e] * scr * qng[128 + i], a2 = f2[e] * scr * qng[160 + i];
;                     float rev = posr * __builtin_amdgcn_exp2f(-(float)i * 0.41524101186092029f); rev -= floorf(rev);
;                     const float sn = __builtin_amdgcn_sinf(rev), cs = __builtin_amdgcn_cosf(rev);
;                     f1[e] = a1 * cs - a2 * sn; f2[e] = a2 * cs + a1 * sn; }
;                 qf[s] = __builtin_bit_cast(bf16x8, pack8(f1)); qf[s + 2] = __builtin_bit_cast(bf16x8, pack8(f2)); }
;             __builtin_amdgcn_sched_barrier(0);
	v_lshl_add_u32 v229, v227, 3, 16
	v_cvt_f32_u32_e32 v229, v229
	v_mul_f32_e32 v229, 0xbed49a78, v229
	v_exp_f32_e32 v229, v229
	v_lshlrev_b32_e32 v234, 16, v148
	v_lshlrev_b32_e32 v235, 16, v156
	v_mul_f32_e32 v229, v240, v229
	v_mul_f32_e32 v234, v234, v242
	v_mul_f32_e32 v235, v235, v242
	v_fract_f32_e32 v229, v229
	v_mul_f32_e32 v234, v234, v182
	v_mul_f32_e32 v235, v235, v190
	v_sin_f32_e32 v230, v229
	v_cos_f32_e32 v231, v229
	s_nop 1
	v_mul_f32_e32 v236, v235, v230
	v_mul_f32_e32 v233, v234, v230
	v_fma_f32 v243, v234, v231, -v236
	v_fma_f32 v245, v235, v231, v233
	v_lshl_add_u32 v229, v227, 3, 17
	v_cvt_f32_u32_e32 v229, v229
	v_mul_f32_e32 v229, 0xbed49a78, v229
	v_exp_f32_e32 v229, v229
	v_and_b32_e32 v234, 0xffff0000, v148
	v_and_b32_e32 v235, 0xffff0000, v156
	v_mul_f32_e32 v229, v240, v229
	v_mul_f32_e32 v234, v234, v242
	v_mul_f32_e32 v235, v235, v242
	v_fract_f32_e32 v229, v229
	v_mul_f32_e32 v234, v234, v183
	v_mul_f32_e32 v235, v235, v191
	v_sin_f32_e32 v230, v229
	v_cos_f32_e32 v231, v229
	s_nop 1
	v_mul_f32_e32 v236, v235, v230
	v_mul_f32_e32 v233, v234, v230
	v_fma_f32 v244, v234, v231, -v236
	v_fma_f32 v246, v235, v231, v233
	v_cvt_pk_bf16_f32 v148, v243, v244
	v_cvt_pk_bf16_f32 v156, v245, v246
	v_lshl_add_u32 v229, v227, 3, 18
	v_cvt_f32_u32_e32 v229, v229
	v_mul_f32_e32 v229, 0xbed49a78, v229
	v_exp_f32_e32 v229, v229
	v_lshlrev_b32_e32 v234, 16, v149
	v_lshlrev_b32_e32 v235, 16, v157
	v_mul_f32_e32 v229, v240, v229
	v_mul_f32_e32 v234, v234, v242
	v_mul_f32_e32 v235, v235, v242
	v_fract_f32_e32 v229, v229
	v_mul_f32_e32 v234, v234, v184
	v_mul_f32_e32 v235, v235, v192
	v_sin_f32_e32 v230, v229
	v_cos_f32_e32 v231, v229
	s_nop 1
	v_mul_f32_e32 v236, v235, v230
	v_mul_f32_e32 v233, v234, v230
	v_fma_f32 v243, v234, v231, -v236
	v_fma_f32 v245, v235, v231, v233
	v_lshl_add_u32 v229, v227, 3, 19
	v_cvt_f32_u32_e32 v229, v229
	v_mul_f32_e32 v229, 0xbed49a78, v229
	v_exp_f32_e32 v229, v229
	v_and_b32_e32 v234, 0xffff0000, v149
	v_and_b32_e32 v235, 0xffff0000, v157
	v_mul_f32_e32 v229, v240, v229
	v_mul_f32_e32 v234, v234, v242
	v_mul_f32_e32 v235, v235, v242
	v_fract_f32_e32 v229, v229
	v_mul_f32_e32 v234, v234, v185
	v_mul_f32_e32 v235, v235, v193
	v_sin_f32_e32 v230, v229
	v_cos_f32_e32 v231, v229
	s_nop 1
	v_mul_f32_e32 v236, v235, v230
	v_mul_f32_e32 v233, v234, v230
	v_fma_f32 v244, v234, v231, -v236
	v_fma_f32 v246, v235, v231, v233
	v_cvt_pk_bf16_f32 v149, v243, v244
	v_cvt_pk_bf16_f32 v157, v245, v246
	v_lshl_add_u32 v229, v227, 3, 20
	v_cvt_f32_u32_e32 v229, v229
	v_mul_f32_e32 v229, 0xbed49a78, v229
	v_exp_f32_e32 v229, v229
	v_lshlrev_b32_e32 v234, 16, v150
	v_lshlrev_b32_e32 v235, 16, v158
	v_mul_f32_e32 v229, v240, v229
	v_mul_f32_e32 v234, v234, v242
	v_mul_f32_e32 v235, v235, v242
	v_fract_f32_e32 v229, v229
	v_mul_f32_e32 v234, v234, v186
	v_mul_f32_e32 v235, v235, v194
	v_sin_f32_e32 v230, v229
	v_cos_f32_e32 v231, v229
	s_nop 1
	v_mul_f32_e32 v236, v235, v230
	v_mul_f32_e32 v233, v234, v230
	v_fma_f32 v243, v234, v231, -v236
	v_fma_f32 v245, v235, v231, v233
	v_lshl_add_u32 v229, v227, 3, 21
	v_cvt_f32_u32_e32 v229, v229
	v_mul_f32_e32 v229, 0xbed49a78, v229
	v_exp_f32_e32 v229, v229
	v_and_b32_e32 v234, 0xffff0000, v150
	v_and_b32_e32 v235, 0xffff0000, v158
	v_mul_f32_e32 v229, v240, v229
	v_mul_f32_e32 v234, v234, v242
	v_mul_f32_e32 v235, v235, v242
	v_fract_f32_e32 v229, v229
	v_mul_f32_e32 v234, v234, v187
	v_mul_f32_e32 v235, v235, v195
	v_sin_f32_e32 v230, v229
	v_cos_f32_e32 v231, v229
	s_nop 1
	v_mul_f32_e32 v236, v235, v230
	v_mul_f32_e32 v233, v234, v230
	v_fma_f32 v244, v234, v231, -v236
	v_fma_f32 v246, v235, v231, v233
	v_cvt_pk_bf16_f32 v150, v243, v244
	v_cvt_pk_bf16_f32 v158, v245, v246
	v_lshl_add_u32 v229, v227, 3, 22
	v_cvt_f32_u32_e32 v229, v229
	v_mul_f32_e32 v229, 0xbed49a78, v229
	v_exp_f32_e32 v229, v229
	v_lshlrev_b32_e32 v234, 16, v151
	v_lshlrev_b32_e32 v235, 16, v159
	v_mul_f32_e32 v229, v240, v229
	v_mul_f32_e32 v234, v234, v242
	v_mul_f32_e32 v235, v235, v242
	v_fract_f32_e32 v229, v229
	v_mul_f32_e32 v234, v234, v188
	v_mul_f32_e32 v235, v235, v196
	v_sin_f32_e32 v230, v229
	v_cos_f32_e32 v231, v229
	s_nop 1
	v_mul_f32_e32 v236, v235, v230
	v_mul_f32_e32 v233, v234, v230
	v_fma_f32 v243, v234, v231, -v236
	v_fma_f32 v245, v235, v231, v233
	v_lshl_add_u32 v229, v227, 3, 23
	v_cvt_f32_u32_e32 v229, v229
	v_mul_f32_e32 v229, 0xbed49a78, v229
	v_exp_f32_e32 v229, v229
	v_and_b32_e32 v234, 0xffff0000, v151
	v_and_b32_e32 v235, 0xffff0000, v159
	v_mul_f32_e32 v229, v240, v229
	v_mul_f32_e32 v234, v234, v242
	v_mul_f32_e32 v235, v235, v242
	v_fract_f32_e32 v229, v229
	v_mul_f32_e32 v234, v234, v189
	v_mul_f32_e32 v235, v235, v197
	v_sin_f32_e32 v230, v229
	v_cos_f32_e32 v231, v229
	s_nop 1
	v_mul_f32_e32 v236, v235, v230
	v_mul_f32_e32 v233, v234, v230
	v_fma_f32 v244, v234, v231, -v236
	v_fma_f32 v246, v235, v231, v233
	v_cvt_pk_bf16_f32 v151, v243, v244
	v_cvt_pk_bf16_f32 v159, v245, v246
	s_barrier
	s_bitcmp0_b32 s26, 2
	s_cbranch_scc1 .Lad_nostag
	s_barrier

; template <int DQK, int KA8, int DV, bool BIAS, bool JOINT>
; DI void attn_core(LAS unsigned char* lds, const bf16_t* Qrow, const bf16_t* KpA, int ldkA, const bf16_t* KpB, int ldkB, const bf16_t* Vp, int ldv,
;                   int qb, int wid, int lane, const float* qng  , f32x16 (&O)[DV / 32]) {
;     ...
;     for (int kt = 0; kt < nkt; ++kt) {
;         if (kt + 1 < nkt) gload(kt + 1);
;         if (JOINT && kt <= myc) {
;             LAS unsigned char* kb = lds + (kt & 1) * STG; LAS unsigned char* vb = kb + 64 * KROW;
;             const bool far = (kt * 64 + 63 - q0w <= -91);
;             f32x16 S0, S1;
; #pragma unroll
;             for (int i = 0; i < 16; ++i) { S0[i] = 0.f; S1[i] = 0.f; }
; #pragma unroll
;             for (int s = 0; s < DQK / 16; ++s) {
;                 const bf16x8 k0 = *(LAS const bf16x8*)(kb + koff + 32 * s), k1 = *(LAS const bf16x8*)(kb + koff + 32 * KROW + 32 * s);
;                 S0 = mfma32(k0, qf[s], S0); S1 = mfma32(k1, qf[s], S1);
;             }
;             if (BIAS && !far) {
;                 const int rb = kt * 64 - (q0w + l32) + 128;
; #pragma unroll
;                 for (int i = 0; i < 16; ++i) { const int i0 = rb + crow(i, hh); S0[i] += btab[i0 < 0 ? 0 : i0]; S1[i] += btab[i0 + 32 < 0 ? 0 : i0 + 32]; }
;             }
;             if (mnz) {
; #pragma unroll
;                 for (int i = 0; i < 16; ++i) { S0[i] -= m; S1[i] -= m; }
;             }
;             float mx = fmaxf(S0[0], S1[0]);
; #pragma unroll
;             for (int i = 1; i < 16; ++i) mx = fmaxf(mx, fmaxf(S0[i], S1[i]));
;             mx = fmaxf(mx, __shfl_xor(mx, 32));
;             if (__any(mx > 64.f || (kt == 0 && mx < -64.f))) {
;                 const float dm = (mx > 64.f || (kt == 0 && mx < -64.f)) ? mx : 0.f, alpha = __builtin_amdgcn_exp2f(-dm); m += dm; mnz = true;
;                 l *= alpha;
; #pragma unroll
;                 for (int dt = 0; dt < DV / 32; ++dt) O[dt] *= alpha;
; #pragma unroll
;                 for (int i = 0; i < 16; ++i) { S0[i] -= dm; S1[i] -= dm; }
;             }
;             float ps = 0.f;
; #pragma unroll
;             for (int i = 0; i < 16; ++i) { S0[i] = __builtin_amdgcn_exp2f(S0[i]); S1[i] = __builtin_amdgcn_exp2f(S1[i]); ps += S0[i] + S1[i]; }
;             l += ps;
; #pragma unroll
;             for (int half = 0; half < 2; ++half)
; #pragma unroll
;                 for (int s = 0; s < 2; ++s) {
.Lad_loop:
	s_add_i32 s58, s25, 1
	s_cmp_eq_u32 s24, 0
	s_cbranch_scc1 .Lad_x0_qk
	s_cmp_gt_u32 s24, s58
	s_cbranch_scc1 .Lad_x0_none
	s_cmp_eq_u32 s24, s58
	s_cbranch_scc1 .Lad_x0_pv
	ds_read_b64_tr_b16 v[182:183], v215 offset:20480
	ds_read_b64_tr_b16 v[184:185], v215 offset:23040
	ds_read_b64_tr_b16 v[186:187], v215 offset:20544
	ds_read_b64_tr_b16 v[188:189], v215 offset:23104
	ds_read_b64_tr_b16 v[190:191], v215 offset:20608
	ds_read_b64_tr_b16 v[192:193], v215 offset:23168
	ds_read_b64_tr_b16 v[194:195], v215 offset:20672
	ds_read_b64_tr_b16 v[196:197], v215 offset:23232
	ds_read_b64_tr_b16 v[198:199], v215 offset:25600
	ds_read_b64_tr_b16 v[200:201], v215 offset:28160
	ds_read_b64_tr_b16 v[202:203], v215 offset:25664
	ds_read_b64_tr_b16 v[204:205], v215 offset:28224
	s_waitcnt lgkmcnt(10)
	v_mfma_f32_32x32x16_bf16 v[0:15], v[182:185], v[96:99], v[0:15]
	ds_read_b64_tr_b16 v[206:207], v215 offset:25728
	ds_read_b64_tr_b16 v[208:209], v215 offset:28288
	s_waitcnt lgkmcnt(10)
	v_mfma_f32_32x32x16_bf16 v[16:31], v[186:189], v[96:99], v[16:31]
	ds_read_b64_tr_b16 v[210:211], v215 offset:25792
	ds_read_b64_tr_b16 v[212:213], v215 offset:28352
	s_waitcnt lgkmcnt(10)
	v_mfma_f32_32x32x16_bf16 v[32:47], v[190:193], v[96:99], v[32:47]
	ds_read_b64_tr_b16 v[182:183], v215 offset:30720
	ds_read_b64_tr_b16 v[184:185], v215 offset:33280
	s_waitcnt lgkmcnt(10)
	v_mfma_f32_32x32x16_bf16 v[48:63], v[194:197], v[96:99], v[48:63]
	s_waitcnt vmcnt(0)
	ds_write_b128 v253, v[160:163] offset:0
	ds_read_b64_tr_b16 v[186:187], v215 offset:30784
	ds_read_b64_tr_b16 v[188:189], v215 offset:33344
	s_waitcnt lgkmcnt(11)
	v_mfma_f32_32x32x16_bf16 v[0:15], v[198:201], v[100:103], v[0:15]
	ds_write_b128 v253, v[164:167] offset:16896
	ds_read_b64_tr_b16 v[190:191], v215 offset:30848
	ds_read_b64_tr_b16 v[192:193], v215 offset:33408
	s_waitcnt lgkmcnt(12)
	v_mfma_f32_32x32x16_bf16 v[16:31], v[202:205], v[100:103], v[16:31]
	ds_write_b128 v254, v[168:171] offset:0
	ds_read_b64_tr_b16 v[194:195], v215 offset:30912
	ds_read_b64_tr_b16 v[196:197], v215 offset:33472
	s_waitcnt lgkmcnt(13)
	v_mfma_f32_32x32x16_bf16 v[32:47], v[206:209], v[100:103], v[32:47]
	ds_write_b128 v218, v[172:175] offset:0
	ds_read_b64_tr_b16 v[198:199], v215 offset:35840
	ds_read_b64_tr_b16 v[200:201], v215 offset:38400
	s_waitcnt lgkmcnt(14)
	v_mfma_f32_32x32x16_bf16 v[48:63], v[210:213], v[100:103], v[48:63]
	ds_write_b128 v218, v[176:179] offset:10240
	ds_read_b64_tr_b16 v[202:203], v215 offset:35904
	ds_read_b64_tr_b16 v[204:205], v215 offset:38464
	s_waitcnt lgkmcnt(15)
	v_mfma_f32_32x32x16_bf16 v[0:15], v[182:185], v[104:107], v[0:15]
	global_load_dwordx4 v[172:175], v222, s[34:35]
	ds_read_b64_tr_b16 v[206:207], v215 offset:35968
	ds_read_b64_tr_b16 v[208:209], v215 offset:38528
	s_waitcnt lgkmcnt(14)
	v_mfma_f32_32x32x16_bf16 v[16:31], v[186:189], v[104:107], v[16:31]
	global_load_dwordx4 v[176:179], v223, s[34:35]
	s_add_u32 s34, s34, 0xe0000
	s_addc_u32 s35, s35, 0
	ds_read_b64_tr_b16 v[210:211], v215 offset:36032
	ds_read_b64_tr_b16 v[212:213], v215 offset:38592
	s_waitcnt lgkmcnt(13)
	v_mfma_f32_32x32x16_bf16 v[32:47], v[190:193], v[104:107], v[32:47]
	global_load_dwordx4 v[160:163], v219, s[30:31]
	ds_read_b128 v[182:185], v214 offset:40960
	s_waitcnt lgkmcnt(11)
	v_mfma_f32_32x32x16_bf16 v[48:63], v[194:197], v[104:107], v[48:63]
	global_load_dwordx4 v[164:167], v220, s[30:31]
	s_add_u32 s30, s30, 0xe0000
	s_addc_u32 s31, s31, 0
	ds_read_b128 v[186:189], v214 offset:57856
	s_waitcnt lgkmcnt(9)
	v_mfma_f32_32x32x16_bf16 v[0:15], v[198:201], v[108:111], v[0:15]
	global_load_dwordx4 v[168:171], v221, s[36:37]
	s_add_u32 s36, s36, 0x22000
	s_addc_u32 s37, s37, 0
	ds_read_b128 v[190:193], v214 offset:40992
	s_waitcnt lgkmcnt(7)
	v_mfma_f32_32x32x16_bf16 v[16:31], v[202:205], v[108:111], v[16:31]
	ds_read_b128 v[194:197], v214 offset:57888
	s_waitcnt lgkmcnt(6)
	v_mfma_f32_32x32x16_bf16 v[32:47], v[206:209], v[108:111], v[32:47]
	ds_read_b128 v[198:201], v214 offset:41024
	s_waitcnt lgkmcnt(5)
	v_mfma_f32_32x32x16_bf16 v[48:63], v[210:213], v[108:111], v[48:63]
	ds_read_b128 v[202:205], v214 offset:57920
	s_waitcnt lgkmcnt(5)
	v_mfma_f32_32x32x16_bf16 v[64:79], v[182:185], v[112:115], 0
	ds_read_b128 v[206:209], v214 offset:41056
	s_waitcnt lgkmcnt(5)
	v_mfma_f32_32x32x16_bf16 v[80:95], v[186:189], v[112:115], 0
	ds_read_b128 v[210:213], v214 offset:57952
	s_waitcnt lgkmcnt(5)
	v_mfma_f32_32x32x16_bf16 v[64:79], v[190:193], v[116:119], v[64:79]
	ds_read_b128 v[182:185], v214 offset:41088
	s_waitcnt lgkmcnt(5)
	v_mfma_f32_32x32x16_bf16 v[80:95], v[194:197], v[116:119], v[80:95]
	ds_read_b128 v[186:189], v214 offset:57984
	s_waitcnt lgkmcnt(5)
	v_mfma_f32_32x32x16_bf16 v[64:79], v[198:201], v[120:123], v[64:79]
	ds_read_b128 v[190:193], v214 offset:41120
	s_waitcnt lgkmcnt(5)
	v_mfma_f32_32x32x16_bf16 v[80:95], v[202:205], v[120:123], v[80:95]
	ds_read_b128 v[194:197], v214 offset:58016
	s_waitcnt lgkmcnt(5)
	v_mfma_f32_32x32x16_bf16 v[64:79], v[206:209], v[124:127], v[64:79]
	ds_read_b128 v[198:201], v214 offset:41152
	s_waitcnt lgkmcnt(5)
	v_mfma_f32_32x32x16_bf16 v[80:95], v[210:213], v[124:127], v[80:95]
	ds_read_b128 v[202:205], v214 offset:58048
	s_waitcnt lgkmcnt(5)
	v_mfma_f32_32x32x16_bf16 v[64:79], v[182:185], v[128:131], v[64:79]
	ds_read_b128 v[206:209], v214 offset:41184
	s_waitcnt lgkmcnt(5)
	v_mfma_f32_32x32x16_bf16 v[80:95], v[186:189], v[128:131], v[80:95]
	ds_read_b128 v[210:213], v214 offset:58080
	s_waitcnt lgkmcnt(5)
	v_mfma_f32_32x32x16_bf16 v[64:79], v[190:193], v[132:135], v[64:79]
	ds_read_b128 v[182:185], v214 offset:41216
	s_waitcnt lgkmcnt(5)
; #define LAS __attribute__((address_space(3)))
; DI unsigned pk2(float a, float b) { f32x2 v = {a, b}; bf16v2_t r = __builtin_convertvector(v, bf16v2_t); return __builtin_bit_cast(unsigned, r); }
; DI f32x16 mfma32(bf16x8 a, bf16x8 b, f32x16 c) { return __builtin_amdgcn_mfma_f32_32x32x16_bf16(a, b, c, 0, 0, 0); }
; DI s16x4 trread(LAS unsigned char* p) { return __builtin_amdgcn_ds_read_tr16_b64_v4i16((LAS s16x4*)p); }
; DI bf16x8 cat4(s16x4 lo, s16x4 hi) { return __builtin_shufflevector(lo, hi, 0, 1, 2, 3, 4, 5, 6, 7); }
; template <int DQK, int KA8, int DV, bool BIAS, bool JOINT>
; DI void attn_core(LAS unsigned char* lds, const bf16_t* Qrow, const bf16_t* KpA, int ldkA, const bf16_t* KpB, int ldkB, const bf16_t* Vp, int ldv,
;                   int qb, int wid, int lane, const float* qng  , f32x16 (&O)[DV / 32]) {
;     ...
;     auto lstore = [&](int buf) {
; #pragma unroll
;         for (int i = 0; i < NL; ++i) { const int c = tid + i * 512;
;             if (i * 512 < NKC) { const int row = c / KC, cc = c % KC; *(LAS u32x4*)(lds + buf * STG + row * KROW + cc * 16) = stg[i]; }
;             else { const int c2 = c - NKC, row = c2 / VC, cc = c2 % VC; *(LAS u32x4*)(lds + buf * STG + 64 * KROW + row * VROW + cc * 16) = stg[i]; } }
;     ...
; #pragma unroll
;             for (int half = 0; half < 2; ++half)
; #pragma unroll
;                 for (int s = 0; s < 2; ++s) {
;                     const f32x16& S = half ? S1 : S0;
;                     u32x4 pw; pw.x = pk2(S[8 * s], S[8 * s + 1]); pw.y = pk2(S[8 * s + 2], S[8 * s + 3]); pw.z = pk2(S[8 * s + 4], S[8 * s + 5]); pw.w = pk2(S[8 * s + 6], S[8 * s + 7]);
;                     const bf16x8 pf = __builtin_bit_cast(bf16x8, pw);
;                     LAS unsigned char* vr = vb + vtr + (32 * half + 16 * s) * VROW;
; #pragma unroll
;                     for (int dt = 0; dt < DV / 32; ++dt) {
;                         const bf16x8 vf = cat4(trread(vr + 64 * dt), trread(vr + 8 * VROW + 64 * dt));
;                         O[dt] = mfma32(vf, pf, O[dt]);
;                     }
	v_mfma_f32_32x32x16_bf16 v[80:95], v[194:197], v[132:135], v[80:95]
	ds_read_b128 v[186:189], v214 offset:58112
	s_waitcnt lgkmcnt(5)
	v_mfma_f32_32x32x16_bf16 v[64:79], v[198:201], v[136:139], v[64:79]
	ds_read_b128 v[190:193], v214 offset:41248
	s_waitcnt lgkmcnt(5)
	v_mfma_f32_32x32x16_bf16 v[80:95], v[202:205], v[136:139], v[80:95]
	ds_read_b128 v[194:197], v214 offset:58144
	s_waitcnt lgkmcnt(5)
	v_mfma_f32_32x32x16_bf16 v[64:79], v[206:209], v[140:143], v[64:79]
	ds_read_b128 v[198:201], v214 offset:41280
	s_waitcnt lgkmcnt(5)
	v_mfma_f32_32x32x16_bf16 v[80:95], v[210:213], v[140:143], v[80:95]
	ds_read_b128 v[202:205], v214 offset:58176
	s_waitcnt lgkmcnt(5)
	v_mfma_f32_32x32x16_bf16 v[64:79], v[182:185], v[144:147], v[64:79]
	ds_read_b128 v[206:209], v214 offset:41312
	s_waitcnt lgkmcnt(5)
	v_mfma_f32_32x32x16_bf16 v[80:95], v[186:189], v[144:147], v[80:95]
	ds_read_b128 v[210:213], v214 offset:58208
	s_waitcnt lgkmcnt(5)
	v_mfma_f32_32x32x16_bf16 v[64:79], v[190:193], v[148:151], v[64:79]
	s_waitcnt lgkmcnt(4)
	v_mfma_f32_32x32x16_bf16 v[80:95], v[194:197], v[148:151], v[80:95]
	s_waitcnt lgkmcnt(3)
	v_mfma_f32_32x32x16_bf16 v[64:79], v[198:201], v[152:155], v[64:79]
	s_waitcnt lgkmcnt(2)
	v_mfma_f32_32x32x16_bf16 v[80:95], v[202:205], v[152:155], v[80:95]
	s_waitcnt lgkmcnt(1)
	v_mfma_f32_32x32x16_bf16 v[64:79], v[206:209], v[156:159], v[64:79]
	s_waitcnt lgkmcnt(0)
	v_mfma_f32_32x32x16_bf16 v[80:95], v[210:213], v[156:159], v[80:95]
	s_branch .Lad_x0_end
.Lad_x0_pv:
	ds_read_b64_tr_b16 v[182:183], v215 offset:20480
	ds_read_b64_tr_b16 v[184:185], v215 offset:23040
	ds_read_b64_tr_b16 v[186:187], v215 offset:20544
	ds_read_b64_tr_b16 v[188:189], v215 offset:23104
	ds_read_b64_tr_b16 v[190:191], v215 offset:20608
	ds_read_b64_tr_b16 v[192:193], v215 offset:23168
	ds_read_b64_tr_b16 v[194:195], v215 offset:20672
	ds_read_b64_tr_b16 v[196:197], v215 offset:23232
	ds_read_b64_tr_b16 v[198:199], v215 offset:25600
	ds_read_b64_tr_b16 v[200:201], v215 offset:28160
	ds_read_b64_tr_b16 v[202:203], v215 offset:25664
	ds_read_b64_tr_b16 v[204:205], v215 offset:28224
	s_waitcnt lgkmcnt(10)
	v_mfma_f32_32x32x16_bf16 v[0:15], v[182:185], v[96:99], v[0:15]
	ds_read_b64_tr_b16 v[206:207], v215 offset:25728
	ds_read_b64_tr_b16 v[208:209], v215 offset:28288
	s_waitcnt lgkmcnt(10)
	v_mfma_f32_32x32x16_bf16 v[16:31], v[186:189], v[96:99], v[16:31]
	ds_read_b64_tr_b16 v[210:211], v215 offset:25792
	ds_read_b64_tr_b16 v[212:213], v215 offset:28352
	s_waitcnt lgkmcnt(10)
	v_mfma_f32_32x32x16_bf16 v[32:47], v[190:193], v[96:99], v[32:47]
	ds_read_b64_tr_b16 v[182:183], v215 offset:30720
	ds_read_b64_tr_b16 v[184:185], v215 offset:33280
	s_waitcnt lgkmcnt(10)
	v_mfma_f32_32x32x16_bf16 v[48:63], v[194:197], v[96:99], v[48:63]
	s_waitcnt vmcnt(0)
	ds_write_b128 v253, v[160:163] offset:0
	ds_read_b64_tr_b16 v[186:187], v215 offset:30784
	ds_read_b64_tr_b16 v[188:189], v215 offset:33344
	s_waitcnt lgkmcnt(11)
	v_mfma_f32_32x32x16_bf16 v[0:15], v[198:201], v[100:103], v[0:15]
	ds_write_b128 v253, v[164:167] offset:16896
	ds_read_b64_tr_b16 v[190:191], v215 offset:30848
	ds_read_b64_tr_b16 v[192:193], v215 offset:33408
	s_waitcnt lgkmcnt(12)
	v_mfma_f32_32x32x16_bf16 v[16:31], v[202:205], v[100:103], v[16:31]
	ds_write_b128 v254, v[168:171] offset:0
	ds_read_b64_tr_b16 v[194:195], v215 offset:30912
	ds_read_b64_tr_b16 v[196:197], v215 offset:33472
	s_waitcnt lgkmcnt(13)
	v_mfma_f32_32x32x16_bf16 v[32:47], v[206:209], v[100:103], v[32:47]
	ds_write_b128 v218, v[172:175] offset:0
	ds_read_b64_tr_b16 v[198:199], v215 offset:35840
	ds_read_b64_tr_b16 v[200:201], v215 offset:38400
	s_waitcnt lgkmcnt(14)
	v_mfma_f32_32x32x16_bf16 v[48:63], v[210:213], v[100:103], v[48:63]
	ds_write_b128 v218, v[176:179] offset:10240
	ds_read_b64_tr_b16 v[202:203], v215 offset:35904
	ds_read_b64_tr_b16 v[204:205], v215 offset:38464
	s_waitcnt lgkmcnt(15)
	v_mfma_f32_32x32x16_bf16 v[0:15], v[182:185], v[104:107], v[0:15]
	global_load_dwordx4 v[172:175], v222, s[34:35]
	ds_read_b64_tr_b16 v[206:207], v215 offset:35968
	ds_read_b64_tr_b16 v[208:209], v215 offset:38528
	s_waitcnt lgkmcnt(14)
	v_mfma_f32_32x32x16_bf16 v[16:31], v[186:189], v[104:107], v[16:31]
	global_load_dwordx4 v[176:179], v223, s[34:35]
	s_add_u32 s34, s34, 0xe0000
	s_addc_u32 s35, s35, 0
	ds_read_b64_tr_b16 v[210:211], v215 offset:36032
	ds_read_b64_tr_b16 v[212:213], v215 offset:38592
	s_waitcnt lgkmcnt(13)
	v_mfma_f32_32x32x16_bf16 v[32:47], v[190:193], v[104:107], v[32:47]
	global_load_dwordx4 v[160:163], v219, s[30:31]
	s_waitcnt lgkmcnt(10)
	v_mfma_f32_32x32x16_bf16 v[48:63], v[194:197], v[104:107], v[48:63]
	global_load_dwordx4 v[164:167], v220, s[30:31]
	s_add_u32 s30, s30, 0xe0000
	s_addc_u32 s31, s31, 0
	s_waitcnt lgkmcnt(7)
	v_mfma_f32_32x32x16_bf16 v[0:15], v[198:201], v[108:111], v[0:15]
	global_load_dwordx4 v[168:171], v221, s[36:37]
	s_add_u32 s36, s36, 0x22000
	s_addc_u32 s37, s37, 0
	s_waitcnt lgkmcnt(4)
	v_mfma_f32_32x32x16_bf16 v[16:31], v[202:205], v[108:111], v[16:31]
	s_waitcnt lgkmcnt(2)
	v_mfma_f32_32x32x16_bf16 v[32:47], v[206:209], v[108:111], v[32:47]
	s_waitcnt lgkmcnt(0)
	v_mfma_f32_32x32x16_bf16 v[48:63], v[210:213], v[108:111], v[48:63]
	s_branch .Lad_x0_end
; #define LAS __attribute__((address_space(3)))
; DI f32x16 mfma32(bf16x8 a, bf16x8 b, f32x16 c) { return __builtin_amdgcn_mfma_f32_32x32x16_bf16(a, b, c, 0, 0, 0); }
; template <int DQK, int KA8, int DV, bool BIAS, bool JOINT>
; DI void attn_core(LAS unsigned char* lds, const bf16_t* Qrow, const bf16_t* KpA, int ldkA, const bf16_t* KpB, int ldkB, const bf16_t* Vp, int ldv,
;                   int qb, int wid, int lane, const float* qng  , f32x16 (&O)[DV / 32]) {
;     ...
;     auto gload = [&](int kt) {
; #pragma unroll
;         for (int i = 0; i < NL; ++i) { const int c = tid + i * 512;
;             if (i * 512 < NKC) { const int row = c / KC, cc = c % KC;
;                 const bf16_t* src = (cc < KA8) ? KpA + (size_t)(kt * 64 + row) * ldkA + cc * 8 : KpB + (size_t)(kt * 64 + row) * ldkB + (cc - KA8) * 8;
;                 stg[i] = *(const u32x4*)src; }
;             else { const int c2 = c - NKC, row = c2 / VC, cc = c2 % VC; stg[i] = *(const u32x4*)(Vp + (size_t)(kt * 64 + row) * ldv + cc * 8); } }
;     };
;     auto lstore = [&](int buf) {
; #pragma unroll
;         for (int i = 0; i < NL; ++i) { const int c = tid + i * 512;
;             if (i * 512 < NKC) { const int row = c / KC, cc = c % KC; *(LAS u32x4*)(lds + buf * STG + row * KROW + cc * 16) = stg[i]; }
;             else { const int c2 = c - NKC, row = c2 / VC, cc = c2 % VC; *(LAS u32x4*)(lds + buf * STG + 64 * KROW + row * VROW + cc * 16) = stg[i]; } }
;     };
;     ...
; #pragma unroll
;             for (int s = 0; s < DQK / 16; ++s) {
;                 const bf16x8 k0 = *(LAS const bf16x8*)(kb + koff + 32 * s), k1 = *(LAS const bf16x8*)(kb + koff + 32 * KROW + 32 * s);
;                 S0 = mfma32(k0, qf[s], S0); S1 = mfma32(k1, qf[s], S1);
;             }
.Lad_x0_qk:
	ds_read_b128 v[182:185], v214 offset:40960
	ds_read_b128 v[186:189], v214 offset:57856
	ds_read_b128 v[190:193], v214 offset:40992
	ds_read_b128 v[194:197], v214 offset:57888
	ds_read_b128 v[198:201], v214 offset:41024
	ds_read_b128 v[202:205], v214 offset:57920
	s_waitcnt lgkmcnt(5)
	v_mfma_f32_32x32x16_bf16 v[64:79], v[182:185], v[112:115], 0
	ds_read_b128 v[206:209], v214 offset:41056
	s_waitcnt lgkmcnt(5)
	v_mfma_f32_32x32x16_bf16 v[80:95], v[186:189], v[112:115], 0
	ds_read_b128 v[210:213], v214 offset:57952
	s_waitcnt lgkmcnt(5)
	v_mfma_f32_32x32x16_bf16 v[64:79], v[190:193], v[116:119], v[64:79]
	ds_read_b128 v[182:185], v214 offset:41088
	s_waitcnt lgkmcnt(5)
	v_mfma_f32_32x32x16_bf16 v[80:95], v[194:197], v[116:119], v[80:95]
	s_waitcnt vmcnt(0)
	ds_write_b128 v253, v[160:163] offset:0
	ds_read_b128 v[186:189], v214 offset:57984
	s_waitcnt lgkmcnt(6)
	v_mfma_f32_32x32x16_bf16 v[64:79], v[198:201], v[120:123], v[64:79]
	ds_write_b128 v253, v[164:167] offset:16896
	ds_read_b128 v[190:193], v214 offset:41120
	s_waitcnt lgkmcnt(7)
	v_mfma_f32_32x32x16_bf16 v[80:95], v[202:205], v[120:123], v[80:95]
	ds_write_b128 v254, v[168:171] offset:0
	ds_read_b128 v[194:197], v214 offset:58016
	s_waitcnt lgkmcnt(8)
	v_mfma_f32_32x32x16_bf16 v[64:79], v[206:209], v[124:127], v[64:79]
	ds_write_b128 v218, v[172:175] offset:0
	ds_read_b128 v[198:201], v214 offset:41152
	s_waitcnt lgkmcnt(9)
	v_mfma_f32_32x32x16_bf16 v[80:95], v[210:213], v[124:127], v[80:95]
	ds_write_b128 v218, v[176:179] offset:10240
	ds_read_b128 v[202:205], v214 offset:58048
	s_waitcnt lgkmcnt(10)
	v_mfma_f32_32x32x16_bf16 v[64:79], v[182:185], v[128:131], v[64:79]
	global_load_dwordx4 v[172:175], v222, s[34:35]
	ds_read_b128 v[206:209], v214 offset:41184
	s_waitcnt lgkmcnt(9)
	v_mfma_f32_32x32x16_bf16 v[80:95], v[186:189], v[128:131], v[80:95]
	global_load_dwordx4 v[176:179], v223, s[34:35]
	s_add_u32 s34, s34, 0xe0000
	s_addc_u32 s35, s35, 0
	ds_read_b128 v[210:213], v214 offset:58080
	s_waitcnt lgkmcnt(8)
	v_mfma_f32_32x32x16_bf16 v[64:79], v[190:193], v[132:135], v[64:79]
	global_load_dwordx4 v[160:163], v219, s[30:31]
	ds_read_b128 v[182:185], v214 offset:41216
	s_waitcnt lgkmcnt(7)
	v_mfma_f32_32x32x16_bf16 v[80:95], v[194:197], v[132:135], v[80:95]
	global_load_dwordx4 v[164:167], v220, s[30:31]
	s_add_u32 s30, s30, 0xe0000
	s_addc_u32 s31, s31, 0
	ds_read_b128 v[186:189], v214 offset:58112
	s_waitcnt lgkmcnt(6)
	v_mfma_f32_32x32x16_bf16 v[64:79], v[198:201], v[136:139], v[64:79]
	global_load_dwordx4 v[168:171], v221, s[36:37]
	s_add_u32 s36, s36, 0x22000
	s_addc_u32 s37, s37, 0
	ds_read_b128 v[190:193], v214 offset:41248
	s_waitcnt lgkmcnt(5)
	v_mfma_f32_32x32x16_bf16 v[80:95], v[202:205], v[136:139], v[80:95]
	ds_read_b128 v[194:197], v214 offset:58144
	s_waitcnt lgkmcnt(5)
	v_mfma_f32_32x32x16_bf16 v[64:79], v[206:209], v[140:143], v[64:79]
	ds_read_b128 v[198:201], v214 offset:41280
	s_waitcnt lgkmcnt(5)
	v_mfma_f32_32x32x16_bf16 v[80:95], v[210:213], v[140:143], v[80:95]
	ds_read_b128 v[202:205], v214 offset:58176
	s_waitcnt lgkmcnt(5)
	v_mfma_f32_32x32x16_bf16 v[64:79], v[182:185], v[144:147], v[64:79]
	ds_read_b128 v[206:209], v214 offset:41312
	s_waitcnt lgkmcnt(5)
	v_mfma_f32_32x32x16_bf16 v[80:95], v[186:189], v[144:147], v[80:95]
	ds_read_b128 v[210:213], v214 offset:58208
	s_waitcnt lgkmcnt(5)
	v_mfma_f32_32x32x16_bf16 v[64:79], v[190:193], v[148:151], v[64:79]
	s_waitcnt lgkmcnt(4)
	v_mfma_f32_32x32x16_bf16 v[80:95], v[194:197], v[148:151], v[80:95]
	s_waitcnt lgkmcnt(3)
	v_mfma_f32_32x32x16_bf16 v[64:79], v[198:201], v[152:155], v[64:79]
	s_waitcnt lgkmcnt(2)
	v_mfma_f32_32x32x16_bf16 v[80:95], v[202:205], v[152:155], v[80:95]
	s_waitcnt lgkmcnt(1)
	v_mfma_f32_32x32x16_bf16 v[64:79], v[206:209], v[156:159], v[64:79]
	s_waitcnt lgkmcnt(0)
	v_mfma_f32_32x32x16_bf16 v[80:95], v[210:213], v[156:159], v[80:95]
	s_branch .Lad_x0_end
.Lad_x0_none:
	s_waitcnt vmcnt(0)
	ds_write_b128 v253, v[160:163] offset:0
	ds_write_b128 v253, v[164:167] offset:16896
	ds_write_b128 v254, v[168:171] offset:0
	ds_write_b128 v218, v[172:175] offset:0
	ds_write_b128 v218, v[176:179] offset:10240
	global_load_dwordx4 v[172:175], v222, s[34:35]
	global_load_dwordx4 v[176:179], v223, s[34:35]
	s_add_u32 s34, s34, 0xe0000
	s_addc_u32 s35, s35, 0
	global_load_dwordx4 v[160:163], v219, s[30:31]
	global_load_dwordx4 v[164:167], v220, s[30:31]
	s_add_u32 s30, s30, 0xe0000
	s_addc_u32 s31, s31, 0
	global_load_dwordx4 v[168:171], v221, s[36:37]
	s_add_u32 s36, s36, 0x22000
	s_addc_u32 s37, s37, 0

; template <int DQK, int KA8, int DV, bool BIAS, bool JOINT>
; DI void attn_core(LAS unsigned char* lds, const bf16_t* Qrow, const bf16_t* KpA, int ldkA, const bf16_t* KpB, int ldkB, const bf16_t* Vp, int ldv,
;                   int qb, int wid, int lane, const float* qng  , f32x16 (&O)[DV / 32]) {
;     ...
;     for (int kt = 0; kt < nkt; ++kt) {
;         if (kt + 1 < nkt) gload(kt + 1);
;         if (JOINT && kt <= myc) {
;             LAS unsigned char* kb = lds + (kt & 1) * STG; LAS unsigned char* vb = kb + 64 * KROW;
;             const bool far = (kt * 64 + 63 - q0w <= -91);
;             f32x16 S0, S1;
; #pragma unroll
;             for (int i = 0; i < 16; ++i) { S0[i] = 0.f; S1[i] = 0.f; }
; #pragma unroll
;             for (int s = 0; s < DQK / 16; ++s) {
;                 const bf16x8 k0 = *(LAS const bf16x8*)(kb + koff + 32 * s), k1 = *(LAS const bf16x8*)(kb + koff + 32 * KROW + 32 * s);
;                 S0 = mfma32(k0, qf[s], S0); S1 = mfma32(k1, qf[s], S1);
;             }
;             if (BIAS && !far) {
;                 const int rb = kt * 64 - (q0w + l32) + 128;
; #pragma unroll
;                 for (int i = 0; i < 16; ++i) { const int i0 = rb + crow(i, hh); S0[i] += btab[i0 < 0 ? 0 : i0]; S1[i] += btab[i0 + 32 < 0 ? 0 : i0 + 32]; }
;             }
;             if (mnz) {
; #pragma unroll
;                 for (int i = 0; i < 16; ++i) { S0[i] -= m; S1[i] -= m; }
;             }
;             float mx = fmaxf(S0[0], S1[0]);
; #pragma unroll
;             for (int i = 1; i < 16; ++i) mx = fmaxf(mx, fmaxf(S0[i], S1[i]));
;             mx = fmaxf(mx, __shfl_xor(mx, 32));
;             if (__any(mx > 64.f || (kt == 0 && mx < -64.f))) {
;                 const float dm = (mx > 64.f || (kt == 0 && mx < -64.f)) ? mx : 0.f, alpha = __builtin_amdgcn_exp2f(-dm); m += dm; mnz = true;
;                 l *= alpha;
; #pragma unroll
;                 for (int dt = 0; dt < DV / 32; ++dt) O[dt] *= alpha;
; #pragma unroll
;                 for (int i = 0; i < 16; ++i) { S0[i] -= dm; S1[i] -= dm; }
;             }
;             float ps = 0.f;
; #pragma unroll
;             for (int i = 0; i < 16; ++i) { S0[i] = __builtin_amdgcn_exp2f(S0[i]); S1[i] = __builtin_amdgcn_exp2f(S1[i]); ps += S0[i] + S1[i]; }
;             l += ps;
; #pragma unroll
;             for (int half = 0; half < 2; ++half)
; #pragma unroll
;                 for (int s = 0; s < 2; ++s) {
.Lad_y0_end:
	s_barrier
	s_add_i32 s59, s24, 1
	s_add_i32 s58, s25, 1
	s_cmp_gt_u32 s59, s58
	s_cbranch_scc1 .Lad_x1_none
	s_cmp_eq_u32 s59, s58
	s_cbranch_scc1 .Lad_x1_pv
	ds_read_b64_tr_b16 v[182:183], v215 offset:0
	ds_read_b64_tr_b16 v[184:185], v215 offset:2560
	ds_read_b64_tr_b16 v[186:187], v215 offset:64
	ds_read_b64_tr_b16 v[188:189], v215 offset:2624
	ds_read_b64_tr_b16 v[190:191], v215 offset:128
	ds_read_b64_tr_b16 v[192:193], v215 offset:2688
	ds_read_b64_tr_b16 v[194:195], v215 offset:192
	ds_read_b64_tr_b16 v[196:197], v215 offset:2752
	ds_read_b64_tr_b16 v[198:199], v215 offset:5120
	ds_read_b64_tr_b16 v[200:201], v215 offset:7680
	ds_read_b64_tr_b16 v[202:203], v215 offset:5184
	ds_read_b64_tr_b16 v[204:205], v215 offset:7744
	s_waitcnt lgkmcnt(10)
	v_mfma_f32_32x32x16_bf16 v[0:15], v[182:185], v[96:99], v[0:15]
	ds_read_b64_tr_b16 v[206:207], v215 offset:5248
	ds_read_b64_tr_b16 v[208:209], v215 offset:7808
	s_waitcnt lgkmcnt(10)
	v_mfma_f32_32x32x16_bf16 v[16:31], v[186:189], v[96:99], v[16:31]
	ds_read_b64_tr_b16 v[210:211], v215 offset:5312
	ds_read_b64_tr_b16 v[212:213], v215 offset:7872
	s_waitcnt lgkmcnt(10)
	v_mfma_f32_32x32x16_bf16 v[32:47], v[190:193], v[96:99], v[32:47]
	ds_read_b64_tr_b16 v[182:183], v215 offset:10240
	ds_read_b64_tr_b16 v[184:185], v215 offset:12800
	s_waitcnt lgkmcnt(10)
	v_mfma_f32_32x32x16_bf16 v[48:63], v[194:197], v[96:99], v[48:63]
	s_waitcnt vmcnt(0)
	ds_write_b128 v216, v[160:163] offset:40960
	ds_read_b64_tr_b16 v[186:187], v215 offset:10304
	ds_read_b64_tr_b16 v[188:189], v215 offset:12864
	s_waitcnt lgkmcnt(11)
	v_mfma_f32_32x32x16_bf16 v[0:15], v[198:201], v[100:103], v[0:15]
	ds_write_b128 v216, v[164:167] offset:57856
	ds_read_b64_tr_b16 v[190:191], v215 offset:10368
	ds_read_b64_tr_b16 v[192:193], v215 offset:12928
	s_waitcnt lgkmcnt(12)
	v_mfma_f32_32x32x16_bf16 v[16:31], v[202:205], v[100:103], v[16:31]
	ds_write_b128 v217, v[168:171] offset:40960
	ds_read_b64_tr_b16 v[194:195], v215 offset:10432
	ds_read_b64_tr_b16 v[196:197], v215 offset:12992
	s_waitcnt lgkmcnt(13)
	v_mfma_f32_32x32x16_bf16 v[32:47], v[206:209], v[100:103], v[32:47]
	ds_write_b128 v218, v[172:175] offset:20480
	ds_read_b64_tr_b16 v[198:199], v215 offset:15360
	ds_read_b64_tr_b16 v[200:201], v215 offset:17920
	s_waitcnt lgkmcnt(14)
	v_mfma_f32_32x32x16_bf16 v[48:63], v[210:213], v[100:103], v[48:63]
	ds_write_b128 v218, v[176:179] offset:30720
	ds_read_b64_tr_b16 v[202:203], v215 offset:15424
	ds_read_b64_tr_b16 v[204:205], v215 offset:17984
	s_waitcnt lgkmcnt(15)
	v_mfma_f32_32x32x16_bf16 v[0:15], v[182:185], v[104:107], v[0:15]
	global_load_dwordx4 v[172:175], v222, s[34:35]
	ds_read_b64_tr_b16 v[206:207], v215 offset:15488
	ds_read_b64_tr_b16 v[208:209], v215 offset:18048
	s_waitcnt lgkmcnt(14)
	v_mfma_f32_32x32x16_bf16 v[16:31], v[186:189], v[104:107], v[16:31]
	global_load_dwordx4 v[176:179], v223, s[34:35]
	s_add_u32 s34, s34, 0xe0000
	s_addc_u32 s35, s35, 0
	ds_read_b64_tr_b16 v[210:211], v215 offset:15552
	ds_read_b64_tr_b16 v[212:213], v215 offset:18112
	s_waitcnt lgkmcnt(13)
	v_mfma_f32_32x32x16_bf16 v[32:47], v[190:193], v[104:107], v[32:47]
	global_load_dwordx4 v[160:163], v219, s[30:31]
	ds_read_b128 v[182:185], v252 offset:0
	s_waitcnt lgkmcnt(11)
	v_mfma_f32_32x32x16_bf16 v[48:63], v[194:197], v[104:107], v[48:63]
	global_load_dwordx4 v[164:167], v220, s[30:31]
	s_add_u32 s30, s30, 0xe0000
	s_addc_u32 s31, s31, 0
	ds_read_b128 v[186:189], v252 offset:16896
	s_waitcnt lgkmcnt(9)
	v_mfma_f32_32x32x16_bf16 v[0:15], v[198:201], v[108:111], v[0:15]
	global_load_dwordx4 v[168:171], v221, s[36:37]
	s_add_u32 s36, s36, 0x22000
	s_addc_u32 s37, s37, 0
	ds_read_b128 v[190:193], v252 offset:32
	s_waitcnt lgkmcnt(7)
	v_mfma_f32_32x32x16_bf16 v[16:31], v[202:205], v[108:111], v[16:31]
	ds_read_b128 v[194:197], v252 offset:16928
	s_waitcnt lgkmcnt(6)
	v_mfma_f32_32x32x16_bf16 v[32:47], v[206:209], v[108:111], v[32:47]
	ds_read_b128 v[198:201], v252 offset:64
	s_waitcnt lgkmcnt(5)
	v_mfma_f32_32x32x16_bf16 v[48:63], v[210:213], v[108:111], v[48:63]
	ds_read_b128 v[202:205], v252 offset:16960
	s_waitcnt lgkmcnt(5)
	v_mfma_f32_32x32x16_bf16 v[64:79], v[182:185], v[112:115], 0
	ds_read_b128 v[206:209], v252 offset:96
	s_waitcnt lgkmcnt(5)
	v_mfma_f32_32x32x16_bf16 v[80:95], v[186:189], v[112:115], 0
	ds_read_b128 v[210:213], v252 offset:16992
	s_waitcnt lgkmcnt(5)
	v_mfma_f32_32x32x16_bf16 v[64:79], v[190:193], v[116:119], v[64:79]
	ds_read_b128 v[182:185], v252 offset:128
	s_waitcnt lgkmcnt(5)
	v_mfma_f32_32x32x16_bf16 v[80:95], v[194:197], v[116:119], v[80:95]
	ds_read_b128 v[186:189], v252 offset:17024
	s_waitcnt lgkmcnt(5)
	v_mfma_f32_32x32x16_bf16 v[64:79], v[198:201], v[120:123], v[64:79]
	ds_read_b128 v[190:193], v252 offset:160
	s_waitcnt lgkmcnt(5)
	v_mfma_f32_32x32x16_bf16 v[80:95], v[202:205], v[120:123], v[80:95]
	ds_read_b128 v[194:197], v252 offset:17056
	s_waitcnt lgkmcnt(5)
	v_mfma_f32_32x32x16_bf16 v[64:79], v[206:209], v[124:127], v[64:79]
	ds_read_b128 v[198:201], v252 offset:192
	s_waitcnt lgkmcnt(5)
	v_mfma_f32_32x32x16_bf16 v[80:95], v[210:213], v[124:127], v[80:95]
	ds_read_b128 v[202:205], v252 offset:17088
	s_waitcnt lgkmcnt(5)
	v_mfma_f32_32x32x16_bf16 v[64:79], v[182:185], v[128:131], v[64:79]
	ds_read_b128 v[206:209], v252 offset:224
	s_waitcnt lgkmcnt(5)
	v_mfma_f32_32x32x16_bf16 v[80:95], v[186:189], v[128:131], v[80:95]
	ds_read_b128 v[210:213], v252 offset:17120
	s_waitcnt lgkmcnt(5)
	v_mfma_f32_32x32x16_bf16 v[64:79], v[190:193], v[132:135], v[64:79]
	ds_read_b128 v[182:185], v252 offset:256
	s_waitcnt lgkmcnt(5)
; #define LAS __attribute__((address_space(3)))
; DI unsigned pk2(float a, float b) { f32x2 v = {a, b}; bf16v2_t r = __builtin_convertvector(v, bf16v2_t); return __builtin_bit_cast(unsigned, r); }
; DI f32x16 mfma32(bf16x8 a, bf16x8 b, f32x16 c) { return __builtin_amdgcn_mfma_f32_32x32x16_bf16(a, b, c, 0, 0, 0); }
; DI s16x4 trread(LAS unsigned char* p) { return __builtin_amdgcn_ds_read_tr16_b64_v4i16((LAS s16x4*)p); }
; DI bf16x8 cat4(s16x4 lo, s16x4 hi) { return __builtin_shufflevector(lo, hi, 0, 1, 2, 3, 4, 5, 6, 7); }
; template <int DQK, int KA8, int DV, bool BIAS, bool JOINT>
; DI void attn_core(LAS unsigned char* lds, const bf16_t* Qrow, const bf16_t* KpA, int ldkA, const bf16_t* KpB, int ldkB, const bf16_t* Vp, int ldv,
;                   int qb, int wid, int lane, const float* qng  , f32x16 (&O)[DV / 32]) {
;     ...
;     auto lstore = [&](int buf) {
; #pragma unroll
;         for (int i = 0; i < NL; ++i) { const int c = tid + i * 512;
;             if (i * 512 < NKC) { const int row = c / KC, cc = c % KC; *(LAS u32x4*)(lds + buf * STG + row * KROW + cc * 16) = stg[i]; }
;             else { const int c2 = c - NKC, row = c2 / VC, cc = c2 % VC; *(LAS u32x4*)(lds + buf * STG + 64 * KROW + row * VROW + cc * 16) = stg[i]; } }
;     ...
; #pragma unroll
;             for (int half = 0; half < 2; ++half)
; #pragma unroll
;                 for (int s = 0; s < 2; ++s) {
;                     const f32x16& S = half ? S1 : S0;
;                     u32x4 pw; pw.x = pk2(S[8 * s], S[8 * s + 1]); pw.y = pk2(S[8 * s + 2], S[8 * s + 3]); pw.z = pk2(S[8 * s + 4], S[8 * s + 5]); pw.w = pk2(S[8 * s + 6], S[8 * s + 7]);
;                     const bf16x8 pf = __builtin_bit_cast(bf16x8, pw);
;                     LAS unsigned char* vr = vb + vtr + (32 * half + 16 * s) * VROW;
; #pragma unroll
;                     for (int dt = 0; dt < DV / 32; ++dt) {
;                         const bf16x8 vf = cat4(trread(vr + 64 * dt), trread(vr + 8 * VROW + 64 * dt));
;                         O[dt] = mfma32(vf, pf, O[dt]);
;                     }
	v_mfma_f32_32x32x16_bf16 v[80:95], v[194:197], v[132:135], v[80:95]
	ds_read_b128 v[186:189], v252 offset:17152
	s_waitcnt lgkmcnt(5)
	v_mfma_f32_32x32x16_bf16 v[64:79], v[198:201], v[136:139], v[64:79]
	ds_read_b128 v[190:193], v252 offset:288
	s_waitcnt lgkmcnt(5)
	v_mfma_f32_32x32x16_bf16 v[80:95], v[202:205], v[136:139], v[80:95]
	ds_read_b128 v[194:197], v252 offset:17184
	s_waitcnt lgkmcnt(5)
	v_mfma_f32_32x32x16_bf16 v[64:79], v[206:209], v[140:143], v[64:79]
	ds_read_b128 v[198:201], v252 offset:320
	s_waitcnt lgkmcnt(5)
	v_mfma_f32_32x32x16_bf16 v[80:95], v[210:213], v[140:143], v[80:95]
	ds_read_b128 v[202:205], v252 offset:17216
	s_waitcnt lgkmcnt(5)
	v_mfma_f32_32x32x16_bf16 v[64:79], v[182:185], v[144:147], v[64:79]
	ds_read_b128 v[206:209], v252 offset:352
	s_waitcnt lgkmcnt(5)
	v_mfma_f32_32x32x16_bf16 v[80:95], v[186:189], v[144:147], v[80:95]
	ds_read_b128 v[210:213], v252 offset:17248
	s_waitcnt lgkmcnt(5)
	v_mfma_f32_32x32x16_bf16 v[64:79], v[190:193], v[148:151], v[64:79]
	s_waitcnt lgkmcnt(4)
	v_mfma_f32_32x32x16_bf16 v[80:95], v[194:197], v[148:151], v[80:95]
	s_waitcnt lgkmcnt(3)
	v_mfma_f32_32x32x16_bf16 v[64:79], v[198:201], v[152:155], v[64:79]
	s_waitcnt lgkmcnt(2)
	v_mfma_f32_32x32x16_bf16 v[80:95], v[202:205], v[152:155], v[80:95]
	s_waitcnt lgkmcnt(1)
	v_mfma_f32_32x32x16_bf16 v[64:79], v[206:209], v[156:159], v[64:79]
	s_waitcnt lgkmcnt(0)
	v_mfma_f32_32x32x16_bf16 v[80:95], v[210:213], v[156:159], v[80:95]
	s_branch .Lad_x1_end
.Lad_x1_pv:
	ds_read_b64_tr_b16 v[182:183], v215 offset:0
	ds_read_b64_tr_b16 v[184:185], v215 offset:2560
	ds_read_b64_tr_b16 v[186:187], v215 offset:64
	ds_read_b64_tr_b16 v[188:189], v215 offset:2624
	ds_read_b64_tr_b16 v[190:191], v215 offset:128
	ds_read_b64_tr_b16 v[192:193], v215 offset:2688
	ds_read_b64_tr_b16 v[194:195], v215 offset:192
	ds_read_b64_tr_b16 v[196:197], v215 offset:2752
	ds_read_b64_tr_b16 v[198:199], v215 offset:5120
	ds_read_b64_tr_b16 v[200:201], v215 offset:7680
	ds_read_b64_tr_b16 v[202:203], v215 offset:5184
	ds_read_b64_tr_b16 v[204:205], v215 offset:7744
	s_waitcnt lgkmcnt(10)
	v_mfma_f32_32x32x16_bf16 v[0:15], v[182:185], v[96:99], v[0:15]
	ds_read_b64_tr_b16 v[206:207], v215 offset:5248
	ds_read_b64_tr_b16 v[208:209], v215 offset:7808
	s_waitcnt lgkmcnt(10)
	v_mfma_f32_32x32x16_bf16 v[16:31], v[186:189], v[96:99], v[16:31]
	ds_read_b64_tr_b16 v[210:211], v215 offset:5312
	ds_read_b64_tr_b16 v[212:213], v215 offset:7872
	s_waitcnt lgkmcnt(10)
	v_mfma_f32_32x32x16_bf16 v[32:47], v[190:193], v[96:99], v[32:47]
	ds_read_b64_tr_b16 v[182:183], v215 offset:10240
	ds_read_b64_tr_b16 v[184:185], v215 offset:12800
	s_waitcnt lgkmcnt(10)
	v_mfma_f32_32x32x16_bf16 v[48:63], v[194:197], v[96:99], v[48:63]
	s_waitcnt vmcnt(0)
	ds_write_b128 v216, v[160:163] offset:40960
	ds_read_b64_tr_b16 v[186:187], v215 offset:10304
	ds_read_b64_tr_b16 v[188:189], v215 offset:12864
	s_waitcnt lgkmcnt(11)
	v_mfma_f32_32x32x16_bf16 v[0:15], v[198:201], v[100:103], v[0:15]
	ds_write_b128 v216, v[164:167] offset:57856
	ds_read_b64_tr_b16 v[190:191], v215 offset:10368
	ds_read_b64_tr_b16 v[192:193], v215 offset:12928
	s_waitcnt lgkmcnt(12)
	v_mfma_f32_32x32x16_bf16 v[16:31], v[202:205], v[100:103], v[16:31]
	ds_write_b128 v217, v[168:171] offset:40960
	ds_read_b64_tr_b16 v[194:195], v215 offset:10432
	ds_read_b64_tr_b16 v[196:197], v215 offset:12992
	s_waitcnt lgkmcnt(13)
	v_mfma_f32_32x32x16_bf16 v[32:47], v[206:209], v[100:103], v[32:47]
	ds_write_b128 v218, v[172:175] offset:20480
	ds_read_b64_tr_b16 v[198:199], v215 offset:15360
	ds_read_b64_tr_b16 v[200:201], v215 offset:17920
	s_waitcnt lgkmcnt(14)
	v_mfma_f32_32x32x16_bf16 v[48:63], v[210:213], v[100:103], v[48:63]
	ds_write_b128 v218, v[176:179] offset:30720
	ds_read_b64_tr_b16 v[202:203], v215 offset:15424
	ds_read_b64_tr_b16 v[204:205], v215 offset:17984
	s_waitcnt lgkmcnt(15)
	v_mfma_f32_32x32x16_bf16 v[0:15], v[182:185], v[104:107], v[0:15]
	global_load_dwordx4 v[172:175], v222, s[34:35]
	ds_read_b64_tr_b16 v[206:207], v215 offset:15488
	ds_read_b64_tr_b16 v[208:209], v215 offset:18048
	s_waitcnt lgkmcnt(14)
	v_mfma_f32_32x32x16_bf16 v[16:31], v[186:189], v[104:107], v[16:31]
	global_load_dwordx4 v[176:179], v223, s[34:35]
	s_add_u32 s34, s34, 0xe0000
	s_addc_u32 s35, s35, 0
	ds_read_b64_tr_b16 v[210:211], v215 offset:15552
	ds_read_b64_tr_b16 v[212:213], v215 offset:18112
	s_waitcnt lgkmcnt(13)
	v_mfma_f32_32x32x16_bf16 v[32:47], v[190:193], v[104:107], v[32:47]
	global_load_dwordx4 v[160:163], v219, s[30:31]
	s_waitcnt lgkmcnt(10)
	v_mfma_f32_32x32x16_bf16 v[48:63], v[194:197], v[104:107], v[48:63]
	global_load_dwordx4 v[164:167], v220, s[30:31]
	s_add_u32 s30, s30, 0xe0000
	s_addc_u32 s31, s31, 0
	s_waitcnt lgkmcnt(7)
	v_mfma_f32_32x32x16_bf16 v[0:15], v[198:201], v[108:111], v[0:15]
	global_load_dwordx4 v[168:171], v221, s[36:37]
	s_add_u32 s36, s36, 0x22000
	s_addc_u32 s37, s37, 0
	s_waitcnt lgkmcnt(4)
	v_mfma_f32_32x32x16_bf16 v[16:31], v[202:205], v[108:111], v[16:31]
	s_waitcnt lgkmcnt(2)
	v_mfma_f32_32x32x16_bf16 v[32:47], v[206:209], v[108:111], v[32:47]
	s_waitcnt lgkmcnt(0)
	v_mfma_f32_32x32x16_bf16 v[48:63], v[210:213], v[108:111], v[48:63]
	s_branch .Lad_x1_end
.Lad_x1_none:
	s_waitcnt vmcnt(0)
	ds_write_b128 v216, v[160:163] offset:40960
	ds_write_b128 v216, v[164:167] offset:57856
	ds_write_b128 v217, v[168:171] offset:40960
	ds_write_b128 v218, v[172:175] offset:20480
	ds_write_b128 v218, v[176:179] offset:30720
	global_load_dwordx4 v[172:175], v222, s[34:35]
	global_load_dwordx4 v[176:179], v223, s[34:35]
	s_add_u32 s34, s34, 0xe0000
	s_addc_u32 s35, s35, 0
	global_load_dwordx4 v[160:163], v219, s[30:31]
	global_load_dwordx4 v[164:167], v220, s[30:31]
	s_add_u32 s30, s30, 0xe0000
	s_addc_u32 s31, s31, 0
	global_load_dwordx4 v[168:171], v221, s[36:37]
	s_add_u32 s36, s36, 0x22000
	s_addc_u32 s37, s37, 0

; template <int DQK, int KA8, int DV, bool BIAS, bool JOINT>
; DI void attn_core(LAS unsigned char* lds, const bf16_t* Qrow, const bf16_t* KpA, int ldkA, const bf16_t* KpB, int ldkB, const bf16_t* Vp, int ldv,
;                   int qb, int wid, int lane, const float* qng  , f32x16 (&O)[DV / 32]) {
;     ...
;         if (kt + 1 < nkt) lstore((kt + 1) & 1);
;         __syncthreads();
;     }
;     l += __shfl_xor(l, 32);
.Lad_nofpv:
	s_bitcmp1_b32 s26, 2
	s_cbranch_scc1 .Lad_noea
	s_barrier
